# cache policy: nt hint on the attention output stores (128 short stores) and on the once-read Q fragment loads of both attention prologues
# baseline (speedup 1.0000x reference)
; __device__ __forceinline__ int v_st(int k, int c) { const int kk = (k & ~0xC) | ((k & 4) << 1) | ((k & 8) >> 1); return ((kk >> 3) * 4 + (c >> 5)) * 512 + ((kk & 7) * 32 + (c & 31)) * 2; }
; __device__ __forceinline__ int v_rd_base(int lane) { return ((lane & 3) << 3) | (((lane >> 2) & 3) << 6) | (((lane >> 4) & 1) << 5) | (((lane >> 5) & 1) << 8); }
; #define SLOAD(i, j) do { const long rb_ = KROW(j); sr_[i].vs0 = *(const bf16x8*)(a.V + (rb_ + sr) * LDV + sc); sr_[i].vs1 = *(const bf16x8*)(a.V + (rb_ + 32 + sr) * LDV + sc); \
;     _Pragma("unroll") for (int c_ = 0; c_ < KCH; ++c_) sr_[i].ks[c_] = *(const bf16x8*)(kptr[c_] + rb_ * kld[c_]); } while (0)
; template <int DQK, int DK1, int LDQ, int LDK, int LDKR, int LDV, int NQL, int SDEPTH>
; __device__ __forceinline__ void attn_core(const AttnArgs& a, char* lds, f32x16 (&o)[4]) {
;     ...
;     char* QL = lds + 2 * SHM_V + 2 * SHM_K + 2048 + tid * 16;
;     { const bf16_t* Qw = a.Q + (long)(wid * 32 + r32) * LDQ + hi * 8;
; #pragma unroll
;       for (int d0 = 0; d0 < NQR; ++d0) qr[d0] = *(const bf16x8*)(Qw + d0 * 16);
; #pragma unroll
;       for (int d0 = NQR; d0 < ND0; ++d0) *(bf16x8*)(QL + (d0 - NQR) * 8192) = *(const bf16x8*)(Qw + d0 * 16); }
;     const int sr = tid >> 4, sc = (tid & 15) * 8, vst0 = v_st(sr, sc), vst1 = v_st(32 + sr, sc);
;     const int vb0 = (int)(uintptr_t)V_lds + v_rd_base(lane);
;     const bf16_t* kptr[KCH]; int kld[KCH], kwo[KCH];
; #pragma unroll
;     for (int c = 0; c < KCH; ++c) { const int idx = tid + c * 512, kr_ = idx / CPR, kc = (idx % CPR) * 8;
;         if (kc < DK1) { kptr[c] = a.Kn + (long)kr_ * LDK + kc; kld[c] = LDK; } else { kptr[c] = a.Kr + (long)kr_ * LDKR + (kc - DK1); kld[c] = LDKR; }
;         kwo[c] = kr_ * KP + ((kc * 2) ^ ((kr_ & 7) << 4)); }
;     struct { bf16x8 vs0, vs1, ks[KCH]; } sr_[SDEPTH];
;     int kb[4];
; #pragma unroll
;     for (int m = 0; m < 4; ++m) kb[m] = r32 * KP + ((m * 32 + hi * 16) ^ ((r32 & 7) << 4));
;     ...
;     f32x16 pA0, pA1, pB0, pB1; float mnA, mnB, alA, alB; bf16x8 pa0, pa1, pa2, pa3; const int NT = a.NT;
;     constexpr int SE = 0, SO = SDEPTH - 1;
;     SLOAD(SE, 0); asm volatile("s_waitcnt vmcnt(0)" ::: "memory"); SWRITE(0, SE); __syncthreads();
.LBB0_170:
	v_mov_b32_e32 v14, v159
	s_xor_b64 s[94:95], s[14:15], -1
	s_lshl_b64 s[14:15], s[12:13], 1
	s_add_u32 s12, s87, s14
	v_ashrrev_i32_e32 v0, 31, v14
	v_lshrrev_b32_e32 v0, 29, v0
	s_addc_u32 s13, s68, s15
	v_add_u32_e32 v0, v14, v0
	s_add_u32 s14, s28, s14
	v_ashrrev_i32_e32 v16, 3, v0
	v_and_b32_e32 v0, -8, v0
	s_addc_u32 s15, s29, s15
	v_sub_u32_e32 v17, v14, v0
	v_ashrrev_i32_e32 v164, 4, v14
	v_lshlrev_b32_e32 v0, 3, v17
	v_mov_b64_e32 v[2:3], s[14:15]
	v_mad_i64_i32 v[2:3], s[14:15], v16, s9, v[2:3]
	v_ashrrev_i32_e32 v1, 31, v0
	v_ashrrev_i32_e32 v165, 31, v164
	v_lshlrev_b32_e32 v15, 3, v14
	v_lshl_add_u64 v[166:167], v[0:1], 1, v[2:3]
	v_lshl_add_u64 v[0:1], v[164:165], 0, s[18:19]
	v_mov_b64_e32 v[50:51], s[20:21]
	v_and_b32_e32 v4, 0x78, v15
	v_mad_u64_u32 v[2:3], s[14:15], v0, s9, v[50:51]
	v_mad_i32_i24 v3, v1, s9, v3
	v_lshlrev_b32_e32 v48, 1, v4
	v_mov_b32_e32 v49, v97
	v_lshl_add_u64 v[168:169], v[164:165], 0, 32
	v_lshl_add_u64 v[0:1], v[2:3], 0, v[48:49]
	v_lshl_add_u64 v[2:3], v[168:169], 0, s[18:19]
	v_mad_u64_u32 v[4:5], s[14:15], v2, s9, v[50:51]
	v_mad_i32_i24 v5, v3, s9, v5
	v_lshl_add_u64 v[4:5], v[4:5], 0, v[48:49]
	global_load_dwordx4 v[0:3], v[0:1], off
	s_nop 0
	global_load_dwordx4 v[4:7], v[4:5], off
	v_ashrrev_i32_e32 v12, 1, v14
	v_lshl_add_u64 v[8:9], v[166:167], 0, s[22:23]
	v_bfi_b32 v18, s33, v12, v14
	v_mov_b64_e32 v[12:13], s[12:13]
	global_load_dwordx4 v[8:11], v[8:9], off
	v_mad_i64_i32 v[12:13], s[12:13], v18, s9, v[12:13]
	v_lshrrev_b32_e32 v18, 1, v14
	v_and_b32_e32 v96, 16, v18
	v_lshl_add_u64 v[12:13], v[12:13], 0, v[96:97]
	global_load_dwordx4 v[110:113], v[12:13], off nt
	global_load_dwordx4 v[106:109], v[12:13], off offset:32 nt
	global_load_dwordx4 v[102:105], v[12:13], off offset:64 nt
	global_load_dwordx4 v[98:101], v[12:13], off offset:96 nt
	v_and_b32_e32 v18, 0xfffff0, v164
	v_lshlrev_b32_e32 v19, 1, v164
	v_lshrrev_b32_e32 v20, 1, v164
	v_and_b32_e32 v21, 3, v164
	v_add_u32_e32 v22, 32, v164
	v_and_or_b32 v18, v19, 8, v18
	v_and_or_b32 v19, v20, 4, v21
	v_and_b32_e32 v20, 0xfffff0, v22
	v_lshlrev_b32_e32 v21, 1, v22
	v_bfe_u32 v15, v15, 5, 2
	v_lshrrev_b32_e32 v18, 1, v18
	v_and_or_b32 v20, v21, 8, v20
	v_and_b32_e32 v68, 31, v14
	v_lshlrev_b32_e32 v52, 4, v14
	v_or_b32_e32 v12, v18, v15
	v_lshrrev_b32_e32 v13, 1, v20
	v_lshlrev_b32_e32 v53, 7, v68
	v_and_b32_e32 v54, 0x70, v52
	v_and_b32_e32 v23, 48, v52
	v_lshlrev_b32_e32 v19, 6, v19
	v_lshlrev_b32_e32 v12, 9, v12
	v_or_b32_e32 v13, v13, v15
	v_bitop3_b32 v22, v96, v53, v54 bitop3:0xde
	v_lshlrev_b32_e32 v18, 7, v16
	v_bitop3_b32 v15, v16, v17, 7 bitop3:0x6c
	v_lshlrev_b32_e32 v13, 9, v13
	v_or3_b32 v12, v12, v19, v23
	v_lshl_add_u32 v15, v15, 4, v18
	v_or3_b32 v13, v13, v19, v23
	v_add_u32_e32 v181, 0, v12
	v_add_u32_e32 v186, 0, v22
	v_add_u32_e32 v182, 0, v15
	v_add_u32_e32 v184, 0, v13
	s_waitcnt vmcnt(0)
	v_and_b32_e32 v69, 63, v14
	v_lshl_add_u64 v[64:65], v[164:165], 0, s[88:89]
	v_mad_u64_u32 v[66:67], s[12:13], v64, s9, v[50:51]
	v_mad_i32_i24 v67, v65, s9, v67
	v_lshl_add_u64 v[60:61], v[166:167], 0, s[78:79]
	v_lshl_add_u64 v[64:65], v[66:67], 0, v[48:49]
	s_cmp_lg_u32 0, -1
	s_cselect_b32 s14, 0, 0
	s_waitcnt vmcnt(0)
	ds_write_b128 v181, v[0:3]
	s_waitcnt vmcnt(5)
	ds_write_b128 v184, v[4:7]
	s_waitcnt vmcnt(4)
	ds_write_b128 v182, v[8:11] offset:32768
	s_waitcnt lgkmcnt(0)
	s_barrier
; #define SLOAD(i, j) do { const long rb_ = KROW(j); sr_[i].vs0 = *(const bf16x8*)(a.V + (rb_ + sr) * LDV + sc); sr_[i].vs1 = *(const bf16x8*)(a.V + (rb_ + 32 + sr) * LDV + sc); \
;     _Pragma("unroll") for (int c_ = 0; c_ < KCH; ++c_) sr_[i].ks[c_] = *(const bf16x8*)(kptr[c_] + rb_ * kld[c_]); } while (0)
; #define SWRITE(b, i) do { *(bf16x8*)(V_lds + (b) * SHM_V + vst0) = sr_[i].vs0; *(bf16x8*)(V_lds + (b) * SHM_V + vst1) = sr_[i].vs1; \
;     _Pragma("unroll") for (int c_ = 0; c_ < KCH; ++c_) *(bf16x8*)(K_lds + (b) * SHM_K + kwo[c_]) = sr_[i].ks[c_]; } while (0)
; template <int DQK, int DK1, int LDQ, int LDK, int LDKR, int LDV, int NQL, int SDEPTH>
; __device__ __forceinline__ void attn_core(const AttnArgs& a, char* lds, f32x16 (&o)[4]) {
;     ...
;     f32x16 pA0, pA1, pB0, pB1; float mnA, mnB, alA, alB; bf16x8 pa0, pa1, pa2, pa3; const int NT = a.NT;
;     constexpr int SE = 0, SO = SDEPTH - 1;
;     SLOAD(SE, 0); asm volatile("s_waitcnt vmcnt(0)" ::: "memory"); SWRITE(0, SE); __syncthreads();
;     QKT(pA0, pA1, K_lds); partialSM(pA0, pA1, m_reg, mnA, alA, a.C, a.thr);
;     SLOAD(SO, 1); if (SDEPTH == 2 && 2 < NT) SLOAD(SE, 2);
;     SWRITE(1, SO); __syncthreads();
	ds_read_b128 v[0:3], v186 offset:32768
	ds_read_b128 v[4:7], v186 offset:36864
	s_waitcnt vmcnt(3) lgkmcnt(1)
	v_mfma_f32_32x32x16_bf16 v[32:47], v[0:3], v[110:113], 0
	v_or_b32_e32 v0, 32, v96
	v_bitop3_b32 v0, v0, v53, v54 bitop3:0xde
	v_add_u32_e32 v188, 0, v0
	ds_read_b128 v[0:3], v188 offset:32768
	v_and_b32_e32 v8, 0x3fffffc0, v14
	v_lshl_add_u32 v161, v8, 2, 0
	v_lshlrev_b32_e32 v8, 3, v69
	s_waitcnt lgkmcnt(1)
	v_mfma_f32_32x32x16_bf16 v[16:31], v[4:7], v[110:113], 0
	ds_read_b128 v[4:7], v188 offset:36864
	s_mov_b32 s37, s36
	s_mov_b32 s38, s36
	s_mov_b32 s39, s36
	s_mov_b32 s40, s36
	s_mov_b32 s41, s36
	s_mov_b32 s42, s36
	s_waitcnt vmcnt(2) lgkmcnt(1)
	v_mfma_f32_32x32x16_bf16 v[32:47], v[0:3], v[106:109], v[32:47]
	v_or_b32_e32 v0, 64, v96
	v_bitop3_b32 v0, v0, v53, v54 bitop3:0xde
	v_add_u32_e32 v190, 0, v0
	ds_read_b128 v[0:3], v190 offset:32768
	s_mov_b32 s43, s36
	s_mov_b32 s44, s36
	s_mov_b32 s45, s36
	s_waitcnt lgkmcnt(1)
	v_mfma_f32_32x32x16_bf16 v[16:31], v[4:7], v[106:109], v[16:31]
	v_and_b32_e32 v4, 0xc0, v52
	v_lshlrev_b32_e32 v5, 1, v14
	v_and_or_b32 v4, v8, 24, v4
	v_and_b32_e32 v5, 32, v5
	v_and_b32_e32 v6, 0x100, v8
	v_or3_b32 v70, v4, v5, v6
	ds_read_b128 v[4:7], v190 offset:36864
	s_waitcnt vmcnt(1) lgkmcnt(1)
	v_mfma_f32_32x32x16_bf16 v[32:47], v[0:3], v[102:105], v[32:47]
	v_or_b32_e32 v0, 0x60, v96
	v_bitop3_b32 v0, v0, v53, v54 bitop3:0xde
	v_add_u32_e32 v192, 0, v0
	ds_read_b128 v[0:3], v192 offset:32768
	ds_read_b128 v[52:55], v192 offset:36864
	s_mov_b32 s46, s36
	s_mov_b32 s47, s36
	s_waitcnt lgkmcnt(2)
	v_mfma_f32_32x32x16_bf16 v[16:31], v[4:7], v[102:105], v[16:31]
	s_mov_b32 s48, s36
	s_mov_b32 s49, s36
	s_mov_b32 s50, s36
	s_mov_b32 s51, s36
	v_add_u32_e32 v180, s14, v70
	v_lshl_add_u64 v[170:171], s[20:21], 0, v[48:49]
	s_mov_b32 s52, 4
	s_waitcnt vmcnt(0) lgkmcnt(1)
	v_mfma_f32_32x32x16_bf16 v[32:47], v[0:3], v[98:101], v[32:47]
	v_mov_b64_e32 v[0:1], s[36:37]
	v_mov_b64_e32 v[14:15], s[50:51]
	v_mov_b64_e32 v[2:3], s[38:39]
	v_mov_b64_e32 v[4:5], s[40:41]
	v_mov_b64_e32 v[6:7], s[42:43]
	v_mov_b64_e32 v[8:9], s[44:45]
	v_mov_b64_e32 v[10:11], s[46:47]
	s_waitcnt lgkmcnt(0)
	v_mfma_f32_32x32x16_bf16 v[16:31], v[52:55], v[98:101], v[16:31]
	s_nop 2
	v_max_f32_e32 v52, v33, v33
	v_max_f32_e32 v53, v32, v32
	v_max_f32_e32 v52, v53, v52
	v_max3_f32 v52, v52, v34, v35
	v_max3_f32 v52, v52, v36, v37
	v_max3_f32 v52, v52, v38, v39
	v_max3_f32 v52, v52, v40, v41
	v_max3_f32 v52, v52, v42, v43
	v_max3_f32 v52, v52, v44, v45
	v_max3_f32 v52, v52, v46, v47
	v_max3_f32 v52, v52, v16, v17
	v_max3_f32 v71, v52, v18, v19
	v_lshl_add_u64 v[52:53], v[164:165], 0, s[24:25]
	v_mad_u64_u32 v[54:55], s[12:13], v52, s9, v[50:51]
	v_mad_i32_i24 v55, v53, s9, v55
	v_lshl_add_u64 v[52:53], v[54:55], 0, v[48:49]
	v_lshl_add_u64 v[54:55], v[168:169], 0, s[24:25]
	v_mad_u64_u32 v[56:57], s[12:13], v54, s9, v[50:51]
	v_mad_i32_i24 v57, v55, s9, v57
	v_lshl_add_u64 v[56:57], v[56:57], 0, v[48:49]
	global_load_dwordx4 v[52:55], v[52:53], off
	s_nop 0
	global_load_dwordx4 v[56:59], v[56:57], off
	v_mov_b64_e32 v[12:13], s[48:49]
	global_load_dwordx4 v[60:63], v[60:61], off
	v_lshl_add_u32 v177, v68, 2, v161
	global_load_dwordx4 v[114:117], v[64:65], off
	v_lshl_add_u64 v[64:65], v[168:169], 0, s[88:89]
	v_mad_u64_u32 v[50:51], s[12:13], v64, s9, v[50:51]
	v_mad_i32_i24 v51, v65, s9, v51
	v_lshl_add_u64 v[50:51], v[50:51], 0, v[48:49]
	v_lshl_add_u64 v[64:65], v[166:167], 0, s[90:91]
	global_load_dwordx4 v[118:121], v[50:51], off
	global_load_dwordx4 v[122:125], v[64:65], off
	v_max3_f32 v50, v71, v20, v21
	v_max3_f32 v50, v50, v22, v23
	v_max3_f32 v50, v50, v24, v25
	v_max3_f32 v50, v50, v26, v27
	v_max3_f32 v50, v50, v28, v29
	v_max3_f32 v50, v50, v30, v31
	v_mov_b32_e32 v51, v50
	s_nop 1
	v_permlane32_swap_b32_e32 v50, v51
	v_max_f32_e32 v51, v51, v51
	v_max_f32_e32 v50, v50, v50
	v_max_f32_e32 v50, v50, v51
	v_add_f32_e32 v51, 0x7149f2ca, v50
	v_max_f32_e32 v50, 0xf149f2ca, v50
	v_cmp_ge_f32_e32 vcc, s76, v51
	v_sub_f32_e32 v51, 0xf149f2ca, v50
	v_mul_f32_e32 v51, 0x3e38aa3b, v51
	v_exp_f32_e32 v51, v51
	s_cmp_eq_u64 vcc, exec
	s_cselect_b64 vcc, -1, 0
	v_cndmask_b32_e32 v142, v50, v193, vcc
	v_mul_f32_e32 v50, 0xbe38aa3b, v142
	v_cndmask_b32_e64 v194, v51, 1.0, vcc
	v_mov_b32_e32 v51, v50
	v_fmamk_f32 v32, v32, 0x3e38aa3b, v50
	v_fmamk_f32 v33, v33, 0x3e38aa3b, v50
	v_fmamk_f32 v34, v34, 0x3e38aa3b, v50
	v_fmamk_f32 v35, v35, 0x3e38aa3b, v50
	v_fmamk_f32 v36, v36, 0x3e38aa3b, v50
	v_fmamk_f32 v37, v37, 0x3e38aa3b, v50
	v_fmamk_f32 v38, v38, 0x3e38aa3b, v50
	v_fmamk_f32 v39, v39, 0x3e38aa3b, v50
	v_fmamk_f32 v40, v40, 0x3e38aa3b, v50
	v_fmamk_f32 v41, v41, 0x3e38aa3b, v50
	v_fmamk_f32 v42, v42, 0x3e38aa3b, v50
	v_fmamk_f32 v43, v43, 0x3e38aa3b, v50
	v_fmamk_f32 v44, v44, 0x3e38aa3b, v50
	v_fmamk_f32 v45, v45, 0x3e38aa3b, v50
	v_fmamk_f32 v46, v46, 0x3e38aa3b, v50
	v_fmac_f32_e32 v51, 0x3e38aa3b, v47
	v_exp_f32_e32 v217, v32
	v_exp_f32_e32 v219, v33
	v_exp_f32_e32 v208, v34
	v_exp_f32_e32 v218, v35
	v_exp_f32_e32 v153, v36
	v_exp_f32_e32 v216, v37
	v_exp_f32_e32 v152, v38
	v_exp_f32_e32 v202, v39
	v_exp_f32_e32 v149, v40
	v_exp_f32_e32 v151, v41
	v_exp_f32_e32 v147, v42
	v_exp_f32_e32 v150, v43
	v_exp_f32_e32 v145, v44
	v_exp_f32_e32 v148, v45
	v_exp_f32_e32 v144, v46
	v_exp_f32_e32 v146, v51
	v_pk_fma_f32 v[132:133], v[30:31], s[8:9], v[50:51] op_sel_hi:[1,0,0]
	v_pk_fma_f32 v[134:135], v[28:29], s[8:9], v[50:51] op_sel_hi:[1,0,0]
	v_pk_fma_f32 v[140:141], v[26:27], s[8:9], v[50:51] op_sel_hi:[1,0,0]
	v_pk_fma_f32 v[126:127], v[24:25], s[8:9], v[50:51] op_sel_hi:[1,0,0]
	v_pk_fma_f32 v[128:129], v[22:23], s[8:9], v[50:51] op_sel_hi:[1,0,0]
	v_pk_fma_f32 v[130:131], v[20:21], s[8:9], v[50:51] op_sel_hi:[1,0,0]
	v_pk_fma_f32 v[136:137], v[18:19], s[8:9], v[50:51] op_sel_hi:[1,0,0]
	v_pk_fma_f32 v[138:139], v[16:17], s[8:9], v[50:51] op_sel_hi:[1,0,0]
	s_waitcnt vmcnt(5)
	ds_write_b128 v181, v[52:55] offset:16384
	s_waitcnt vmcnt(4)
	ds_write_b128 v184, v[56:59] offset:16384
	s_waitcnt vmcnt(3)
	ds_write_b128 v182, v[60:63] offset:40960
	s_addk_i32 s14, 0x4000
	v_mov_b64_e32 v[30:31], v[14:15]
	v_mov_b64_e32 v[46:47], v[14:15]
	v_mov_b64_e32 v[62:63], v[14:15]
	v_cmp_gt_u32_e64 s[12:13], 32, v69
	v_add_u32_e32 v179, s14, v70
	v_mov_b32_e32 v178, 0
	v_mov_b64_e32 v[28:29], v[12:13]
	v_mov_b64_e32 v[26:27], v[10:11]
	v_mov_b64_e32 v[24:25], v[8:9]
	v_mov_b64_e32 v[22:23], v[6:7]
	v_mov_b64_e32 v[20:21], v[4:5]
	v_mov_b64_e32 v[18:19], v[2:3]
	v_mov_b64_e32 v[16:17], v[0:1]
	v_mov_b64_e32 v[44:45], v[12:13]
	v_mov_b64_e32 v[42:43], v[10:11]
	v_mov_b64_e32 v[40:41], v[8:9]
	v_mov_b64_e32 v[38:39], v[6:7]
	v_mov_b64_e32 v[36:37], v[4:5]
	v_mov_b64_e32 v[34:35], v[2:3]
	v_mov_b64_e32 v[32:33], v[0:1]
	v_mov_b64_e32 v[60:61], v[12:13]
	v_mov_b64_e32 v[58:59], v[10:11]
	v_mov_b64_e32 v[56:57], v[8:9]
	v_mov_b64_e32 v[54:55], v[6:7]
	v_mov_b64_e32 v[52:53], v[4:5]
	v_mov_b64_e32 v[50:51], v[2:3]
	v_mov_b64_e32 v[48:49], v[0:1]
	s_waitcnt lgkmcnt(0)
	s_barrier

; __device__ __forceinline__ void partialSM(f32x16& p0, f32x16& p1, float& m_reg, float& mn, float& alpha, const float C, const float thr) {
;     ...
;     else { mn = fmaxf(m_reg, pmax); alpha = __builtin_amdgcn_exp2f((m_reg - mn) * C); m_reg = mn; }
;     const float mnC = -mn * C;
; #pragma unroll
;     for (int r = 0; r < 16; ++r) p0[r] = fmaf(p0[r], C, mnC);
; #pragma unroll
;     for (int r = 0; r < 16; ++r) p1[r] = fmaf(p1[r], C, mnC);
; #pragma unroll
;     for (int r = 0; r < 16; ++r) p0[r] = __builtin_amdgcn_exp2f(p0[r]);
; }
; __device__ __forceinline__ void finishSM(f32x16& p0, f32x16& p1, float alpha, float& l_reg, bf16x8& pa0, bf16x8& pa1, bf16x8& pa2, bf16x8& pa3) {
; #pragma unroll
;     for (int r = 0; r < 16; ++r) p1[r] = __builtin_amdgcn_exp2f(p1[r]);
;     float ps = 0;
; #pragma unroll
;     for (int r = 0; r < 16; ++r) ps += p0[r];
; #pragma unroll
;     for (int r = 0; r < 16; ++r) ps += p1[r];
;     { auto rr = __builtin_amdgcn_permlane32_swap(__float_as_uint(ps), __float_as_uint(ps), false, false);
;       ps = __uint_as_float(rr[0]) + __uint_as_float(rr[1]); }
;     l_reg = l_reg * alpha + ps;
;     ...
;     PK4(p0, 0, pa0); PK4(p0, 8, pa1); PK4(p1, 0, pa2); PK4(p1, 8, pa3);
;     ...
; }
.LBB0_187:
	v_cndmask_b32_e64 v101, v101, v142, s[14:15]
	v_mul_f32_e32 v101, 0xbe38aa3b, v101
	v_fmamk_f32 v80, v80, 0x3e38aa3b, v101
	v_fmamk_f32 v81, v81, 0x3e38aa3b, v101
	v_fmamk_f32 v102, v82, 0x3e38aa3b, v101
	v_exp_f32_e32 v82, v80
	v_fmamk_f32 v103, v84, 0x3e38aa3b, v101
	v_exp_f32_e32 v84, v81
	v_fmamk_f32 v83, v83, 0x3e38aa3b, v101
	v_exp_f32_e32 v80, v102
	v_fmamk_f32 v64, v64, 0x3e38aa3b, v101
	v_exp_f32_e32 v83, v83
	v_fmamk_f32 v104, v85, 0x3e38aa3b, v101
	v_fmamk_f32 v113, v94, 0x3e38aa3b, v101
	v_fmamk_f32 v94, v75, 0x3e38aa3b, v101
	v_exp_f32_e32 v75, v103
	v_exp_f32_e32 v102, v64
	v_add_f32_e32 v64, 0, v82
	v_fmamk_f32 v105, v86, 0x3e38aa3b, v101
	v_exp_f32_e32 v81, v104
	v_add_f32_e32 v64, v84, v64
	v_fmamk_f32 v106, v87, 0x3e38aa3b, v101
	v_fmamk_f32 v112, v93, 0x3e38aa3b, v101
	v_fmamk_f32 v93, v74, 0x3e38aa3b, v101
	v_exp_f32_e32 v74, v105
	v_add_f32_e32 v64, v80, v64
	v_fmamk_f32 v107, v88, 0x3e38aa3b, v101
	v_fmamk_f32 v114, v95, 0x3e38aa3b, v101
	v_fmamk_f32 v95, v76, 0x3e38aa3b, v101
	v_exp_f32_e32 v76, v106
	v_add_f32_e32 v64, v83, v64
	v_fmamk_f32 v108, v89, 0x3e38aa3b, v101
	v_fmamk_f32 v109, v90, 0x3e38aa3b, v101
	v_fmamk_f32 v90, v71, 0x3e38aa3b, v101
	v_exp_f32_e32 v71, v107
	v_add_f32_e32 v64, v75, v64
	v_fmamk_f32 v111, v92, 0x3e38aa3b, v101
	v_fmamk_f32 v92, v73, 0x3e38aa3b, v101
	v_exp_f32_e32 v73, v108
	v_add_f32_e32 v64, v81, v64
	v_fmamk_f32 v110, v91, 0x3e38aa3b, v101
	v_fmamk_f32 v88, v69, 0x3e38aa3b, v101
	v_exp_f32_e32 v69, v109
	v_add_f32_e32 v64, v74, v64
	v_fmamk_f32 v91, v72, 0x3e38aa3b, v101
	v_exp_f32_e32 v72, v110
	v_add_f32_e32 v64, v76, v64
	v_fmamk_f32 v86, v67, 0x3e38aa3b, v101
	v_exp_f32_e32 v67, v111
	v_add_f32_e32 v64, v71, v64
	v_fmamk_f32 v89, v70, 0x3e38aa3b, v101
	v_exp_f32_e32 v70, v112
	v_add_f32_e32 v64, v73, v64
	v_fmamk_f32 v85, v66, 0x3e38aa3b, v101
	v_exp_f32_e32 v66, v113
	v_add_f32_e32 v64, v69, v64
	v_fmamk_f32 v87, v68, 0x3e38aa3b, v101
	v_exp_f32_e32 v68, v114
	v_add_f32_e32 v64, v72, v64
	v_fmamk_f32 v65, v65, 0x3e38aa3b, v101
	v_add_f32_e32 v64, v67, v64
	v_exp_f32_e32 v103, v65
	v_add_f32_e32 v64, v70, v64
	v_exp_f32_e32 v85, v85
	v_add_f32_e32 v64, v66, v64
	v_exp_f32_e32 v86, v86
	v_add_f32_e32 v64, v68, v64
	v_exp_f32_e32 v87, v87
	v_add_f32_e32 v64, v102, v64
	v_exp_f32_e32 v88, v88
	v_add_f32_e32 v64, v103, v64
	v_exp_f32_e32 v89, v89
	v_add_f32_e32 v64, v85, v64
	v_exp_f32_e32 v90, v90
	v_add_f32_e32 v64, v86, v64
	v_exp_f32_e32 v91, v91
	v_add_f32_e32 v64, v87, v64
	v_exp_f32_e32 v92, v92
	v_add_f32_e32 v64, v88, v64
	v_exp_f32_e32 v93, v93
	v_add_f32_e32 v64, v89, v64
	v_exp_f32_e32 v94, v94
	v_add_f32_e32 v64, v90, v64
	v_fmamk_f32 v77, v77, 0x3e38aa3b, v101
	v_exp_f32_e32 v95, v95
	v_add_f32_e32 v64, v91, v64
	v_fmamk_f32 v78, v78, 0x3e38aa3b, v101
	v_exp_f32_e32 v104, v77
	v_add_f32_e32 v64, v92, v64
	v_fmac_f32_e32 v101, 0x3e38aa3b, v79
	v_exp_f32_e32 v105, v78
	v_add_f32_e32 v64, v93, v64
	v_exp_f32_e32 v101, v101
	v_add_f32_e32 v64, v94, v64
	v_add_f32_e32 v64, v95, v64
	v_add_f32_e32 v64, v104, v64
	v_add_f32_e32 v64, v105, v64
	v_add_f32_e32 v64, v101, v64
	v_mov_b32_e32 v65, v64
	s_nop 1
	v_permlane32_swap_b32_e32 v64, v65
	v_cvt_pk_bf16_f32 v78, v82, v84
	v_cvt_pk_bf16_f32 v79, v80, v83
	v_cvt_pk_bf16_f32 v80, v75, v81
	v_cvt_pk_bf16_f32 v81, v74, v76
	v_cvt_pk_bf16_f32 v74, v71, v73
	v_cvt_pk_bf16_f32 v75, v69, v72
	v_cvt_pk_bf16_f32 v76, v67, v70
	v_cvt_pk_bf16_f32 v77, v66, v68
	v_cvt_pk_bf16_f32 v66, v102, v103
	v_cvt_pk_bf16_f32 v67, v85, v86
	v_cvt_pk_bf16_f32 v68, v87, v88
	v_cvt_pk_bf16_f32 v69, v89, v90
	v_cvt_pk_bf16_f32 v70, v91, v92
	v_cvt_pk_bf16_f32 v71, v93, v94
	v_cvt_pk_bf16_f32 v72, v95, v104
	v_cvt_pk_bf16_f32 v73, v105, v101
	s_nop 0
	v_permlane32_swap_b32_e32 v78, v80
	v_permlane32_swap_b32_e32 v79, v81
	v_permlane32_swap_b32_e32 v74, v76
	v_permlane32_swap_b32_e32 v75, v77
	v_permlane32_swap_b32_e32 v66, v68
	v_permlane32_swap_b32_e32 v67, v69
	v_permlane32_swap_b32_e32 v70, v72
	v_permlane32_swap_b32_e32 v71, v73
	ds_read_b64_tr_b16 v[82:83], v179 offset:0
	ds_read_b64_tr_b16 v[84:85], v179 offset:0x800
	ds_read_b64_tr_b16 v[86:87], v179 offset:0x1000
	ds_read_b64_tr_b16 v[88:89], v179 offset:0x1800
	ds_read_b64_tr_b16 v[90:91], v179 offset:0x2000
	ds_read_b64_tr_b16 v[92:93], v179 offset:0x2800
	ds_read_b64_tr_b16 v[102:103], v179 offset:0x3000
	ds_read_b64_tr_b16 v[104:105], v179 offset:0x3800
	s_waitcnt lgkmcnt(0)
	s_nop 0
	v_mfma_f32_32x32x16_bf16 v[48:63], v[78:81], v[82:85], v[48:63]
	ds_read_b64_tr_b16 v[82:83], v179 offset:0x200
	ds_read_b64_tr_b16 v[84:85], v179 offset:0xa00
	v_mfma_f32_32x32x16_bf16 v[48:63], v[74:77], v[86:89], v[48:63]
	ds_read_b64_tr_b16 v[86:87], v179 offset:0x1200
	ds_read_b64_tr_b16 v[88:89], v179 offset:0x1a00
	v_mfma_f32_32x32x16_bf16 v[48:63], v[66:69], v[90:93], v[48:63]
	ds_read_b64_tr_b16 v[90:91], v179 offset:0x2200
	ds_read_b64_tr_b16 v[92:93], v179 offset:0x2a00
	v_mfma_f32_32x32x16_bf16 v[48:63], v[70:73], v[102:105], v[48:63]
	ds_read_b64_tr_b16 v[102:103], v179 offset:0x3200
	ds_read_b64_tr_b16 v[104:105], v179 offset:0x3a00
	s_waitcnt lgkmcnt(0)
	v_mfma_f32_32x32x16_bf16 v[32:47], v[78:81], v[82:85], v[32:47]
	ds_read_b64_tr_b16 v[82:83], v179 offset:0x400
	ds_read_b64_tr_b16 v[84:85], v179 offset:0xc00
	v_mfma_f32_32x32x16_bf16 v[32:47], v[74:77], v[86:89], v[32:47]
	ds_read_b64_tr_b16 v[86:87], v179 offset:0x1400
	ds_read_b64_tr_b16 v[88:89], v179 offset:0x1c00
	v_mfma_f32_32x32x16_bf16 v[32:47], v[66:69], v[90:93], v[32:47]
	ds_read_b64_tr_b16 v[90:91], v179 offset:0x2400
	ds_read_b64_tr_b16 v[92:93], v179 offset:0x2c00
	v_mfma_f32_32x32x16_bf16 v[32:47], v[70:73], v[102:105], v[32:47]
	ds_read_b64_tr_b16 v[102:103], v179 offset:0x3400
	ds_read_b64_tr_b16 v[104:105], v179 offset:0x3c00
	s_waitcnt lgkmcnt(0)
; __device__ __forceinline__ int crow(int r, int hi) { return (r & 3) + 8 * (r >> 2) + 4 * hi; }
; template <int DQK, int DK1, int LDQ, int LDK, int LDKR, int LDV, int NQL, int SDEPTH>
; __device__ __forceinline__ void attn_core(const AttnArgs& a, char* lds, f32x16 (&o)[4]) {
;     ...
;     pv_d0(o, vb0 + SHM_V, pa0, pa1, pa2, pa3);
;     if (hi == 0) li_l[r32] = l_reg; asm volatile("s_waitcnt lgkmcnt(0)" ::: "memory");
; #pragma unroll
;     for (int r = 0; r < 16; ++r) { const float rl = __builtin_amdgcn_rcpf(li_l[crow(r, hi)]);
; #pragma unroll
;         for (int d = 0; d < 4; ++d) o[d][r] *= rl; }
;     __syncthreads();
; __device__ __forceinline__ void phase_attn_diff(const Params& p, char* lds) {
;     ...
;             float* scr = scr0; asm volatile("" : "+v"(scr));
;             if (j == 0) {
; #pragma unroll
;                 for (int r = 0; r < 16; ++r) { f32x4 t = {o[0][r], o[1][r], o[2][r], o[3][r]}; *(f32x4*)(scr + 4 * r) = t; }
	v_mfma_f32_32x32x16_bf16 v[16:31], v[78:81], v[82:85], v[16:31]
	ds_read_b64_tr_b16 v[82:83], v179 offset:0x600
	ds_read_b64_tr_b16 v[84:85], v179 offset:0xe00
	v_mfma_f32_32x32x16_bf16 v[16:31], v[74:77], v[86:89], v[16:31]
	ds_read_b64_tr_b16 v[86:87], v179 offset:0x1600
	ds_read_b64_tr_b16 v[88:89], v179 offset:0x1e00
	v_mfma_f32_32x32x16_bf16 v[16:31], v[66:69], v[90:93], v[16:31]
	ds_read_b64_tr_b16 v[90:91], v179 offset:0x2600
	ds_read_b64_tr_b16 v[92:93], v179 offset:0x2e00
	v_mfma_f32_32x32x16_bf16 v[16:31], v[70:73], v[102:105], v[16:31]
	ds_read_b64_tr_b16 v[102:103], v179 offset:0x3600
	ds_read_b64_tr_b16 v[104:105], v179 offset:0x3e00
	s_waitcnt lgkmcnt(0)
	v_mfma_f32_32x32x16_bf16 v[0:15], v[78:81], v[82:85], v[0:15]
	v_mfma_f32_32x32x16_bf16 v[0:15], v[74:77], v[86:89], v[0:15]
	v_mfma_f32_32x32x16_bf16 v[0:15], v[66:69], v[90:93], v[0:15]
	v_mfma_f32_32x32x16_bf16 v[0:15], v[70:73], v[102:105], v[0:15]
	s_and_saveexec_b64 s[14:15], s[12:13]
	v_add_f32_e32 v66, v98, v99
	v_fmac_f32_e32 v66, v178, v143
	v_add_f32_e32 v64, v64, v65
	v_fmac_f32_e32 v64, v66, v100
	ds_write_b32 v177, v64 offset:49152
	s_or_b64 exec, exec, s[14:15]
	s_waitcnt lgkmcnt(0)
	v_add_u32_e32 v82, v161, v96
	ds_read_b128 v[74:77], v82 offset:49152
	ds_read_b128 v[78:81], v82 offset:49184
	v_mov_b32_e32 v68, v16
	s_nop 0
	v_mov_b32_e32 v69, v0
	v_mov_b32_e32 v0, v17
	s_waitcnt lgkmcnt(1)
	v_rcp_f32_e32 v16, v75
	v_rcp_f32_e32 v66, v74
	v_mov_b32_e32 v64, v48
	v_mov_b32_e32 v65, v32
	v_pk_mul_f32 v[70:71], v[0:1], v[16:17] op_sel_hi:[1,0]
	v_rcp_f32_e32 v0, v76
	v_mov_b32_e32 v32, v49
	v_pk_mul_f32 v[64:65], v[64:65], v[66:67] op_sel_hi:[1,0]
	v_pk_mul_f32 v[66:67], v[68:69], v[66:67] op_sel_hi:[1,0]
	v_pk_mul_f32 v[68:69], v[32:33], v[16:17] op_sel_hi:[1,0]
	v_mov_b32_e32 v16, v50
	v_mov_b32_e32 v17, v34
	v_pk_mul_f32 v[72:73], v[16:17], v[0:1] op_sel_hi:[1,0]
	v_mov_b32_e32 v16, v18
	v_mov_b32_e32 v17, v2
	v_pk_mul_f32 v[74:75], v[16:17], v[0:1] op_sel_hi:[1,0]
	v_rcp_f32_e32 v16, v77
	v_mov_b32_e32 v32, v20
	s_waitcnt lgkmcnt(0)
	v_rcp_f32_e32 v20, v79
	v_mov_b32_e32 v34, v51
	v_rcp_f32_e32 v18, v78
	v_mov_b32_e32 v33, v4
	v_mov_b32_e32 v4, v21
	v_pk_mul_f32 v[0:1], v[34:35], v[16:17] op_sel_hi:[1,0]
	v_pk_mul_f32 v[34:35], v[4:5], v[20:21] op_sel_hi:[1,0]
	v_rcp_f32_e32 v4, v80
	ds_read_b128 v[76:79], v82 offset:49216
	v_mov_b32_e32 v2, v19
	v_pk_mul_f32 v[2:3], v[2:3], v[16:17] op_sel_hi:[1,0]
	v_mov_b32_e32 v16, v52
	v_mov_b32_e32 v17, v36
	v_mov_b32_e32 v36, v53
	v_pk_mul_f32 v[16:17], v[16:17], v[18:19] op_sel_hi:[1,0]
	v_pk_mul_f32 v[18:19], v[32:33], v[18:19] op_sel_hi:[1,0]
	v_pk_mul_f32 v[32:33], v[36:37], v[20:21] op_sel_hi:[1,0]
	v_mov_b32_e32 v20, v54
	v_mov_b32_e32 v21, v38
	v_pk_mul_f32 v[48:49], v[20:21], v[4:5] op_sel_hi:[1,0]
	v_mov_b32_e32 v20, v22
	v_mov_b32_e32 v21, v6
	v_pk_mul_f32 v[50:51], v[20:21], v[4:5] op_sel_hi:[1,0]
	v_rcp_f32_e32 v20, v81
	v_mov_b32_e32 v36, v24
	s_waitcnt lgkmcnt(0)
	v_rcp_f32_e32 v24, v77
	v_mov_b32_e32 v38, v55
	v_rcp_f32_e32 v22, v76
	v_mov_b32_e32 v37, v8
	v_mov_b32_e32 v8, v25
	v_pk_mul_f32 v[4:5], v[38:39], v[20:21] op_sel_hi:[1,0]
	v_pk_mul_f32 v[38:39], v[8:9], v[24:25] op_sel_hi:[1,0]
	v_rcp_f32_e32 v8, v78
	v_mov_b32_e32 v6, v23
	v_pk_mul_f32 v[6:7], v[6:7], v[20:21] op_sel_hi:[1,0]
	v_mov_b32_e32 v20, v56
	v_mov_b32_e32 v21, v40
	v_mov_b32_e32 v40, v57
	v_pk_mul_f32 v[20:21], v[20:21], v[22:23] op_sel_hi:[1,0]
	v_pk_mul_f32 v[22:23], v[36:37], v[22:23] op_sel_hi:[1,0]
	v_pk_mul_f32 v[36:37], v[40:41], v[24:25] op_sel_hi:[1,0]
	v_mov_b32_e32 v24, v58
	v_mov_b32_e32 v25, v42
	v_pk_mul_f32 v[52:53], v[24:25], v[8:9] op_sel_hi:[1,0]
	v_mov_b32_e32 v24, v26
	v_mov_b32_e32 v25, v10
	v_pk_mul_f32 v[54:55], v[24:25], v[8:9] op_sel_hi:[1,0]
	v_rcp_f32_e32 v24, v79
	ds_read_b128 v[76:79], v82 offset:49248
	v_mov_b32_e32 v40, v28
	v_mov_b32_e32 v42, v59
	v_mov_b32_e32 v41, v12
	v_mov_b32_e32 v12, v29
	s_waitcnt lgkmcnt(0)
	v_rcp_f32_e32 v28, v77
	v_rcp_f32_e32 v26, v76
	v_pk_mul_f32 v[8:9], v[42:43], v[24:25] op_sel_hi:[1,0]
	v_mov_b32_e32 v10, v27
	v_pk_mul_f32 v[42:43], v[12:13], v[28:29] op_sel_hi:[1,0]
	v_rcp_f32_e32 v12, v78
	v_pk_mul_f32 v[10:11], v[10:11], v[24:25] op_sel_hi:[1,0]
	v_mov_b32_e32 v24, v60
	v_mov_b32_e32 v25, v44
	v_mov_b32_e32 v44, v61
	v_pk_mul_f32 v[24:25], v[24:25], v[26:27] op_sel_hi:[1,0]
	v_pk_mul_f32 v[26:27], v[40:41], v[26:27] op_sel_hi:[1,0]
	v_pk_mul_f32 v[40:41], v[44:45], v[28:29] op_sel_hi:[1,0]
	v_mov_b32_e32 v28, v62
	v_mov_b32_e32 v29, v46
	v_pk_mul_f32 v[56:57], v[28:29], v[12:13] op_sel_hi:[1,0]
	v_mov_b32_e32 v28, v30
	v_mov_b32_e32 v29, v14
	v_pk_mul_f32 v[58:59], v[28:29], v[12:13] op_sel_hi:[1,0]
	v_rcp_f32_e32 v28, v79
	v_mov_b32_e32 v46, v63
	v_mov_b32_e32 v14, v31
	s_mov_b64 s[12:13], -1
	v_pk_mul_f32 v[12:13], v[46:47], v[28:29] op_sel_hi:[1,0]
	v_pk_mul_f32 v[14:15], v[14:15], v[28:29] op_sel_hi:[1,0]
	v_mov_b64_e32 v[28:29], v[154:155]
	s_and_b64 vcc, exec, s[94:95]
	s_barrier
	s_cbranch_vccz .LBB0_191
; __device__ __forceinline__ void phase_attn_diff(const Params& p, char* lds) {
;     ...
;             } else {
;                 bf16_t* Ow = O + (size_t)(row0 + wid * 32 + 4 * hi) * 1024 + h * 128 + r32;
;                 asm volatile("" : "+v"(Ow));
; #pragma unroll
;                 for (int r = 0; r < 16; ++r) {
;                     const f32x4 t = *(const f32x4*)(scr + 4 * r);
;                     const float v0 = t[0] - lam * o[0][r], v1 = t[1] - lam * o[1][r], v2 = t[2] - lam * o[2][r], v3 = t[3] - lam * o[3][r];
;                     float ss = v0 * v0 + v1 * v1 + v2 * v2 + v3 * v3;
	global_load_dwordx4 v[84:87], v[28:29], off
	global_load_dwordx4 v[88:91], v[28:29], off offset:16
	global_load_dwordx4 v[92:95], v[28:29], off offset:32
	global_load_dwordx4 v[100:103], v[28:29], off offset:48
	global_load_dwordx4 v[104:107], v[28:29], off offset:64
	global_load_dwordx4 v[108:111], v[28:29], off offset:80
	global_load_dwordx4 v[112:115], v[28:29], off offset:96
	global_load_dwordx4 v[116:119], v[28:29], off offset:112
	global_load_dwordx4 v[120:123], v[28:29], off offset:128
	global_load_dwordx4 v[124:127], v[28:29], off offset:144
	global_load_dwordx4 v[128:131], v[28:29], off offset:160
	global_load_dwordx4 v[132:135], v[28:29], off offset:176
	global_load_dwordx4 v[136:139], v[28:29], off offset:192
	global_load_dwordx4 v[140:143], v[28:29], off offset:208
	global_load_dwordx4 v[144:147], v[28:29], off offset:224
	global_load_dwordx4 v[148:151], v[28:29], off offset:240
	v_mov_b64_e32 v[30:31], v[162:163]
	v_xor_b32_e32 v44, 16, v183
	v_xor_b32_e32 v45, 8, v183
	v_xor_b32_e32 v46, 4, v183
	v_xor_b32_e32 v47, 2, v183
	v_xor_b32_e32 v60, 1, v183
	v_lshlrev_b32_e32 v44, 2, v44
	v_lshlrev_b32_e32 v45, 2, v45
	v_lshlrev_b32_e32 v46, 2, v46
	v_lshlrev_b32_e32 v47, 2, v47
	v_lshlrev_b32_e32 v60, 2, v60
	s_mov_b32 s2, 0xd000
	s_waitcnt vmcnt(0) lgkmcnt(0)
	v_pk_fma_f32 v[84:85], v[156:157], v[64:65], v[84:85] neg_lo:[1,0,0] neg_hi:[1,0,0]
	v_pk_fma_f32 v[86:87], v[156:157], v[66:67], v[86:87] neg_lo:[1,0,0] neg_hi:[1,0,0]
	v_pk_fma_f32 v[88:89], v[156:157], v[68:69], v[88:89] neg_lo:[1,0,0] neg_hi:[1,0,0]
	v_pk_fma_f32 v[90:91], v[156:157], v[70:71], v[90:91] neg_lo:[1,0,0] neg_hi:[1,0,0]
	v_pk_fma_f32 v[92:93], v[156:157], v[72:73], v[92:93] neg_lo:[1,0,0] neg_hi:[1,0,0]
	v_pk_fma_f32 v[94:95], v[156:157], v[74:75], v[94:95] neg_lo:[1,0,0] neg_hi:[1,0,0]
	v_pk_fma_f32 v[100:101], v[156:157], v[0:1], v[100:101] neg_lo:[1,0,0] neg_hi:[1,0,0]
	v_pk_fma_f32 v[102:103], v[156:157], v[2:3], v[102:103] neg_lo:[1,0,0] neg_hi:[1,0,0]
	v_pk_fma_f32 v[104:105], v[156:157], v[16:17], v[104:105] neg_lo:[1,0,0] neg_hi:[1,0,0]
	v_pk_fma_f32 v[106:107], v[156:157], v[18:19], v[106:107] neg_lo:[1,0,0] neg_hi:[1,0,0]
	v_pk_fma_f32 v[108:109], v[156:157], v[32:33], v[108:109] neg_lo:[1,0,0] neg_hi:[1,0,0]
	v_pk_fma_f32 v[110:111], v[156:157], v[34:35], v[110:111] neg_lo:[1,0,0] neg_hi:[1,0,0]
	v_pk_fma_f32 v[112:113], v[156:157], v[48:49], v[112:113] neg_lo:[1,0,0] neg_hi:[1,0,0]
	v_pk_fma_f32 v[114:115], v[156:157], v[50:51], v[114:115] neg_lo:[1,0,0] neg_hi:[1,0,0]
	v_pk_fma_f32 v[116:117], v[156:157], v[4:5], v[116:117] neg_lo:[1,0,0] neg_hi:[1,0,0]
	v_pk_fma_f32 v[118:119], v[156:157], v[6:7], v[118:119] neg_lo:[1,0,0] neg_hi:[1,0,0]
	v_pk_fma_f32 v[120:121], v[156:157], v[20:21], v[120:121] neg_lo:[1,0,0] neg_hi:[1,0,0]
	v_pk_fma_f32 v[122:123], v[156:157], v[22:23], v[122:123] neg_lo:[1,0,0] neg_hi:[1,0,0]
	v_pk_fma_f32 v[124:125], v[156:157], v[36:37], v[124:125] neg_lo:[1,0,0] neg_hi:[1,0,0]
	v_pk_fma_f32 v[126:127], v[156:157], v[38:39], v[126:127] neg_lo:[1,0,0] neg_hi:[1,0,0]
	v_pk_fma_f32 v[128:129], v[156:157], v[52:53], v[128:129] neg_lo:[1,0,0] neg_hi:[1,0,0]
	v_pk_fma_f32 v[130:131], v[156:157], v[54:55], v[130:131] neg_lo:[1,0,0] neg_hi:[1,0,0]
	v_pk_fma_f32 v[132:133], v[156:157], v[8:9], v[132:133] neg_lo:[1,0,0] neg_hi:[1,0,0]
	v_pk_fma_f32 v[134:135], v[156:157], v[10:11], v[134:135] neg_lo:[1,0,0] neg_hi:[1,0,0]
	v_pk_fma_f32 v[136:137], v[156:157], v[24:25], v[136:137] neg_lo:[1,0,0] neg_hi:[1,0,0]
	v_pk_fma_f32 v[138:139], v[156:157], v[26:27], v[138:139] neg_lo:[1,0,0] neg_hi:[1,0,0]
	v_pk_fma_f32 v[140:141], v[156:157], v[40:41], v[140:141] neg_lo:[1,0,0] neg_hi:[1,0,0]
	v_pk_fma_f32 v[142:143], v[156:157], v[42:43], v[142:143] neg_lo:[1,0,0] neg_hi:[1,0,0]
	v_pk_fma_f32 v[144:145], v[156:157], v[56:57], v[144:145] neg_lo:[1,0,0] neg_hi:[1,0,0]
	v_pk_fma_f32 v[146:147], v[156:157], v[58:59], v[146:147] neg_lo:[1,0,0] neg_hi:[1,0,0]
	v_pk_fma_f32 v[148:149], v[156:157], v[12:13], v[148:149] neg_lo:[1,0,0] neg_hi:[1,0,0]
	v_pk_fma_f32 v[150:151], v[156:157], v[14:15], v[150:151] neg_lo:[1,0,0] neg_hi:[1,0,0]
	v_pk_mul_f32 v[64:65], v[84:85], v[84:85]
	v_pk_mul_f32 v[66:67], v[86:87], v[86:87]
	v_pk_mul_f32 v[68:69], v[88:89], v[88:89]
	v_pk_mul_f32 v[70:71], v[90:91], v[90:91]
	v_pk_mul_f32 v[72:73], v[92:93], v[92:93]
	v_pk_mul_f32 v[74:75], v[94:95], v[94:95]
	v_pk_mul_f32 v[0:1], v[100:101], v[100:101]
	v_pk_mul_f32 v[2:3], v[102:103], v[102:103]
	v_pk_mul_f32 v[16:17], v[104:105], v[104:105]
	v_pk_mul_f32 v[18:19], v[106:107], v[106:107]
	v_pk_mul_f32 v[32:33], v[108:109], v[108:109]
	v_pk_mul_f32 v[34:35], v[110:111], v[110:111]
	v_pk_mul_f32 v[48:49], v[112:113], v[112:113]
	v_pk_mul_f32 v[50:51], v[114:115], v[114:115]
	v_pk_mul_f32 v[4:5], v[116:117], v[116:117]
	v_pk_mul_f32 v[6:7], v[118:119], v[118:119]
	v_pk_mul_f32 v[20:21], v[120:121], v[120:121]
	v_pk_mul_f32 v[22:23], v[122:123], v[122:123]
	v_pk_mul_f32 v[36:37], v[124:125], v[124:125]
	v_pk_mul_f32 v[38:39], v[126:127], v[126:127]
	v_pk_mul_f32 v[52:53], v[128:129], v[128:129]
	v_pk_mul_f32 v[54:55], v[130:131], v[130:131]
	v_pk_mul_f32 v[8:9], v[132:133], v[132:133]
	v_pk_mul_f32 v[10:11], v[134:135], v[134:135]
	v_pk_mul_f32 v[24:25], v[136:137], v[136:137]
	v_pk_mul_f32 v[26:27], v[138:139], v[138:139]
	v_pk_mul_f32 v[40:41], v[140:141], v[140:141]
	v_pk_mul_f32 v[42:43], v[142:143], v[142:143]
	v_pk_mul_f32 v[56:57], v[144:145], v[144:145]
	v_pk_mul_f32 v[58:59], v[146:147], v[146:147]
	v_pk_mul_f32 v[12:13], v[148:149], v[148:149]
	v_pk_mul_f32 v[14:15], v[150:151], v[150:151]
	v_add_f32_e32 v64, v64, v65
	v_add_f32_e32 v68, v68, v69
; __device__ __forceinline__ void phase_attn_diff(const Params& p, char* lds) {
;     ...
;                     float ss = v0 * v0 + v1 * v1 + v2 * v2 + v3 * v3;
; #pragma unroll
;                     for (int x = 16; x >= 1; x >>= 1) ss += __shfl_xor(ss, x);
	v_add_f32_e32 v72, v72, v73
	v_add_f32_e32 v0, v0, v1
	v_add_f32_e32 v16, v16, v17
	v_add_f32_e32 v32, v32, v33
	v_add_f32_e32 v48, v48, v49
	v_add_f32_e32 v4, v4, v5
	v_add_f32_e32 v20, v20, v21
	v_add_f32_e32 v36, v36, v37
	v_add_f32_e32 v52, v52, v53
	v_add_f32_e32 v8, v8, v9
	v_add_f32_e32 v24, v24, v25
	v_add_f32_e32 v40, v40, v41
	v_add_f32_e32 v56, v56, v57
	v_add_f32_e32 v12, v12, v13
	v_add_f32_e32 v64, v66, v64
	v_add_f32_e32 v68, v70, v68
	v_add_f32_e32 v72, v74, v72
	v_add_f32_e32 v0, v2, v0
	v_add_f32_e32 v16, v18, v16
	v_add_f32_e32 v32, v34, v32
	v_add_f32_e32 v48, v50, v48
	v_add_f32_e32 v4, v6, v4
	v_add_f32_e32 v20, v22, v20
	v_add_f32_e32 v36, v38, v36
	v_add_f32_e32 v52, v54, v52
	v_add_f32_e32 v8, v10, v8
	v_add_f32_e32 v24, v26, v24
	v_add_f32_e32 v40, v42, v40
	v_add_f32_e32 v56, v58, v56
	v_add_f32_e32 v12, v14, v12
	v_add_f32_e32 v64, v67, v64
	v_add_f32_e32 v68, v71, v68
	v_add_f32_e32 v72, v75, v72
	v_add_f32_e32 v0, v3, v0
	v_add_f32_e32 v16, v19, v16
	v_add_f32_e32 v32, v35, v32
	v_add_f32_e32 v48, v51, v48
	v_add_f32_e32 v4, v7, v4
	v_add_f32_e32 v20, v23, v20
	v_add_f32_e32 v36, v39, v36
	v_add_f32_e32 v52, v55, v52
	v_add_f32_e32 v8, v11, v8
	v_add_f32_e32 v24, v27, v24
	v_add_f32_e32 v40, v43, v40
	v_add_f32_e32 v56, v59, v56
	v_add_f32_e32 v12, v15, v12
	ds_bpermute_b32 v65, v44, v64
	ds_bpermute_b32 v69, v44, v68
	ds_bpermute_b32 v73, v44, v72
	ds_bpermute_b32 v1, v44, v0
	ds_bpermute_b32 v17, v44, v16
	ds_bpermute_b32 v33, v44, v32
	ds_bpermute_b32 v49, v44, v48
	ds_bpermute_b32 v5, v44, v4
	ds_bpermute_b32 v21, v44, v20
	ds_bpermute_b32 v37, v44, v36
	ds_bpermute_b32 v53, v44, v52
	ds_bpermute_b32 v9, v44, v8
	ds_bpermute_b32 v25, v44, v24
	ds_bpermute_b32 v41, v44, v40
	ds_bpermute_b32 v57, v44, v56
	ds_bpermute_b32 v13, v44, v12
	s_waitcnt lgkmcnt(15)
	v_add_f32_e32 v64, v64, v65
	s_waitcnt lgkmcnt(14)
	v_add_f32_e32 v68, v68, v69
	s_waitcnt lgkmcnt(13)
	v_add_f32_e32 v72, v72, v73
	s_waitcnt lgkmcnt(12)
	v_add_f32_e32 v0, v0, v1
	s_waitcnt lgkmcnt(11)
	v_add_f32_e32 v16, v16, v17
	s_waitcnt lgkmcnt(10)
	v_add_f32_e32 v32, v32, v33
	s_waitcnt lgkmcnt(9)
	v_add_f32_e32 v48, v48, v49
	s_waitcnt lgkmcnt(8)
	v_add_f32_e32 v4, v4, v5
	s_waitcnt lgkmcnt(7)
	v_add_f32_e32 v20, v20, v21
	s_waitcnt lgkmcnt(6)
	v_add_f32_e32 v36, v36, v37
	s_waitcnt lgkmcnt(5)
	v_add_f32_e32 v52, v52, v53
	s_waitcnt lgkmcnt(4)
	v_add_f32_e32 v8, v8, v9
	s_waitcnt lgkmcnt(3)
	v_add_f32_e32 v24, v24, v25
	s_waitcnt lgkmcnt(2)
	v_add_f32_e32 v40, v40, v41
	s_waitcnt lgkmcnt(1)
	v_add_f32_e32 v56, v56, v57
	s_waitcnt lgkmcnt(0)
	v_add_f32_e32 v12, v12, v13
	ds_bpermute_b32 v65, v45, v64
	ds_bpermute_b32 v69, v45, v68
	ds_bpermute_b32 v73, v45, v72
	ds_bpermute_b32 v1, v45, v0
	ds_bpermute_b32 v17, v45, v16
	ds_bpermute_b32 v33, v45, v32
	ds_bpermute_b32 v49, v45, v48
	ds_bpermute_b32 v5, v45, v4
	ds_bpermute_b32 v21, v45, v20
	ds_bpermute_b32 v37, v45, v36
	ds_bpermute_b32 v53, v45, v52
	ds_bpermute_b32 v9, v45, v8
	ds_bpermute_b32 v25, v45, v24
	ds_bpermute_b32 v41, v45, v40
	ds_bpermute_b32 v57, v45, v56
	ds_bpermute_b32 v13, v45, v12
	s_waitcnt lgkmcnt(15)
	v_add_f32_e32 v64, v64, v65
	s_waitcnt lgkmcnt(14)
	v_add_f32_e32 v68, v68, v69
	s_waitcnt lgkmcnt(13)
	v_add_f32_e32 v72, v72, v73
	s_waitcnt lgkmcnt(12)
	v_add_f32_e32 v0, v0, v1
	s_waitcnt lgkmcnt(11)
	v_add_f32_e32 v16, v16, v17
	s_waitcnt lgkmcnt(10)
	v_add_f32_e32 v32, v32, v33
	s_waitcnt lgkmcnt(9)
	v_add_f32_e32 v48, v48, v49
	s_waitcnt lgkmcnt(8)
	v_add_f32_e32 v4, v4, v5
	s_waitcnt lgkmcnt(7)
	v_add_f32_e32 v20, v20, v21
	s_waitcnt lgkmcnt(6)
	v_add_f32_e32 v36, v36, v37
	s_waitcnt lgkmcnt(5)
	v_add_f32_e32 v52, v52, v53
	s_waitcnt lgkmcnt(4)
	v_add_f32_e32 v8, v8, v9
	s_waitcnt lgkmcnt(3)
	v_add_f32_e32 v24, v24, v25
	s_waitcnt lgkmcnt(2)
	v_add_f32_e32 v40, v40, v41
	s_waitcnt lgkmcnt(1)
	v_add_f32_e32 v56, v56, v57
	s_waitcnt lgkmcnt(0)
	v_add_f32_e32 v12, v12, v13
	ds_bpermute_b32 v65, v46, v64
	ds_bpermute_b32 v69, v46, v68
	ds_bpermute_b32 v73, v46, v72
	ds_bpermute_b32 v1, v46, v0
	ds_bpermute_b32 v17, v46, v16
	ds_bpermute_b32 v33, v46, v32
	ds_bpermute_b32 v49, v46, v48
	ds_bpermute_b32 v5, v46, v4
	ds_bpermute_b32 v21, v46, v20
	ds_bpermute_b32 v37, v46, v36
	ds_bpermute_b32 v53, v46, v52
	ds_bpermute_b32 v9, v46, v8
	ds_bpermute_b32 v25, v46, v24
	ds_bpermute_b32 v41, v46, v40
	ds_bpermute_b32 v57, v46, v56
	ds_bpermute_b32 v13, v46, v12
	s_waitcnt lgkmcnt(15)
	v_add_f32_e32 v64, v64, v65
	s_waitcnt lgkmcnt(14)
	v_add_f32_e32 v68, v68, v69
	s_waitcnt lgkmcnt(13)
	v_add_f32_e32 v72, v72, v73
	s_waitcnt lgkmcnt(12)
	v_add_f32_e32 v0, v0, v1
	s_waitcnt lgkmcnt(11)
	v_add_f32_e32 v16, v16, v17
	s_waitcnt lgkmcnt(10)
	v_add_f32_e32 v32, v32, v33
	s_waitcnt lgkmcnt(9)
	v_add_f32_e32 v48, v48, v49
	s_waitcnt lgkmcnt(8)
	v_add_f32_e32 v4, v4, v5
	s_waitcnt lgkmcnt(7)
	v_add_f32_e32 v20, v20, v21
	s_waitcnt lgkmcnt(6)
	v_add_f32_e32 v36, v36, v37
	s_waitcnt lgkmcnt(5)
	v_add_f32_e32 v52, v52, v53
	s_waitcnt lgkmcnt(4)
	v_add_f32_e32 v8, v8, v9
	s_waitcnt lgkmcnt(3)
	v_add_f32_e32 v24, v24, v25
	s_waitcnt lgkmcnt(2)
	v_add_f32_e32 v40, v40, v41
	s_waitcnt lgkmcnt(1)
	v_add_f32_e32 v56, v56, v57
	s_waitcnt lgkmcnt(0)
	v_add_f32_e32 v12, v12, v13
	ds_bpermute_b32 v65, v47, v64
	ds_bpermute_b32 v69, v47, v68
	ds_bpermute_b32 v73, v47, v72
	ds_bpermute_b32 v1, v47, v0
	ds_bpermute_b32 v17, v47, v16
	ds_bpermute_b32 v33, v47, v32
	ds_bpermute_b32 v49, v47, v48
	ds_bpermute_b32 v5, v47, v4
	ds_bpermute_b32 v21, v47, v20
	ds_bpermute_b32 v37, v47, v36
	ds_bpermute_b32 v53, v47, v52
	ds_bpermute_b32 v9, v47, v8
	ds_bpermute_b32 v25, v47, v24
	ds_bpermute_b32 v41, v47, v40
	ds_bpermute_b32 v57, v47, v56
	ds_bpermute_b32 v13, v47, v12
	s_waitcnt lgkmcnt(15)
; __device__ __forceinline__ void phase_attn_diff(const Params& p, char* lds) {
;     ...
;                     for (int x = 16; x >= 1; x >>= 1) ss += __shfl_xor(ss, x);
;                     const float rs = rsqrtf(ss * (1.0f / 128.0f) + EPS);
	v_add_f32_e32 v64, v64, v65
	s_waitcnt lgkmcnt(14)
	v_add_f32_e32 v68, v68, v69
	s_waitcnt lgkmcnt(13)
	v_add_f32_e32 v72, v72, v73
	s_waitcnt lgkmcnt(12)
	v_add_f32_e32 v0, v0, v1
	s_waitcnt lgkmcnt(11)
	v_add_f32_e32 v16, v16, v17
	s_waitcnt lgkmcnt(10)
	v_add_f32_e32 v32, v32, v33
	s_waitcnt lgkmcnt(9)
	v_add_f32_e32 v48, v48, v49
	s_waitcnt lgkmcnt(8)
	v_add_f32_e32 v4, v4, v5
	s_waitcnt lgkmcnt(7)
	v_add_f32_e32 v20, v20, v21
	s_waitcnt lgkmcnt(6)
	v_add_f32_e32 v36, v36, v37
	s_waitcnt lgkmcnt(5)
	v_add_f32_e32 v52, v52, v53
	s_waitcnt lgkmcnt(4)
	v_add_f32_e32 v8, v8, v9
	s_waitcnt lgkmcnt(3)
	v_add_f32_e32 v24, v24, v25
	s_waitcnt lgkmcnt(2)
	v_add_f32_e32 v40, v40, v41
	s_waitcnt lgkmcnt(1)
	v_add_f32_e32 v56, v56, v57
	s_waitcnt lgkmcnt(0)
	v_add_f32_e32 v12, v12, v13
	ds_bpermute_b32 v65, v60, v64
	ds_bpermute_b32 v69, v60, v68
	ds_bpermute_b32 v73, v60, v72
	ds_bpermute_b32 v1, v60, v0
	ds_bpermute_b32 v17, v60, v16
	ds_bpermute_b32 v33, v60, v32
	ds_bpermute_b32 v49, v60, v48
	ds_bpermute_b32 v5, v60, v4
	ds_bpermute_b32 v21, v60, v20
	ds_bpermute_b32 v37, v60, v36
	ds_bpermute_b32 v53, v60, v52
	ds_bpermute_b32 v9, v60, v8
	ds_bpermute_b32 v25, v60, v24
	ds_bpermute_b32 v41, v60, v40
	ds_bpermute_b32 v57, v60, v56
	ds_bpermute_b32 v13, v60, v12
	s_waitcnt lgkmcnt(15)
	v_add_f32_e32 v64, v64, v65
	s_waitcnt lgkmcnt(14)
	v_add_f32_e32 v68, v68, v69
	s_waitcnt lgkmcnt(13)
	v_add_f32_e32 v72, v72, v73
	s_waitcnt lgkmcnt(12)
	v_add_f32_e32 v0, v0, v1
	s_waitcnt lgkmcnt(11)
	v_add_f32_e32 v16, v16, v17
	s_waitcnt lgkmcnt(10)
	v_add_f32_e32 v32, v32, v33
	s_waitcnt lgkmcnt(9)
	v_add_f32_e32 v48, v48, v49
	s_waitcnt lgkmcnt(8)
	v_add_f32_e32 v4, v4, v5
	s_waitcnt lgkmcnt(7)
	v_add_f32_e32 v20, v20, v21
	s_waitcnt lgkmcnt(6)
	v_add_f32_e32 v36, v36, v37
	s_waitcnt lgkmcnt(5)
	v_add_f32_e32 v52, v52, v53
	s_waitcnt lgkmcnt(4)
	v_add_f32_e32 v8, v8, v9
	s_waitcnt lgkmcnt(3)
	v_add_f32_e32 v24, v24, v25
	s_waitcnt lgkmcnt(2)
	v_add_f32_e32 v40, v40, v41
	s_waitcnt lgkmcnt(1)
	v_add_f32_e32 v56, v56, v57
	s_waitcnt lgkmcnt(0)
	v_add_f32_e32 v12, v12, v13
	v_fmamk_f32 v64, v64, 0x3c000000, v158
	v_cmp_gt_f32_e32 vcc, s82, v64
	v_mul_f32_e32 v65, 0x4b800000, v64
	s_nop 0
	v_cndmask_b32_e32 v64, v64, v65, vcc
	v_rsq_f32_e32 v64, v64
	s_nop 0
	v_mul_f32_e32 v65, 0x45800000, v64
	v_cndmask_b32_e32 v64, v64, v65, vcc
	v_fmamk_f32 v68, v68, 0x3c000000, v158
	v_cmp_gt_f32_e32 vcc, s82, v68
	v_mul_f32_e32 v69, 0x4b800000, v68
	s_nop 0
	v_cndmask_b32_e32 v68, v68, v69, vcc
	v_rsq_f32_e32 v68, v68
	s_nop 0
	v_mul_f32_e32 v69, 0x45800000, v68
	v_cndmask_b32_e32 v68, v68, v69, vcc
	v_fmamk_f32 v72, v72, 0x3c000000, v158
	v_cmp_gt_f32_e32 vcc, s82, v72
	v_mul_f32_e32 v73, 0x4b800000, v72
	s_nop 0
	v_cndmask_b32_e32 v72, v72, v73, vcc
	v_rsq_f32_e32 v72, v72
	s_nop 0
	v_mul_f32_e32 v73, 0x45800000, v72
	v_cndmask_b32_e32 v72, v72, v73, vcc
	v_fmamk_f32 v0, v0, 0x3c000000, v158
	v_cmp_gt_f32_e32 vcc, s82, v0
	v_mul_f32_e32 v1, 0x4b800000, v0
	s_nop 0
	v_cndmask_b32_e32 v0, v0, v1, vcc
	v_rsq_f32_e32 v0, v0
	s_nop 0
	v_mul_f32_e32 v1, 0x45800000, v0
	v_cndmask_b32_e32 v0, v0, v1, vcc
	v_fmamk_f32 v16, v16, 0x3c000000, v158
	v_cmp_gt_f32_e32 vcc, s82, v16
	v_mul_f32_e32 v17, 0x4b800000, v16
	s_nop 0
	v_cndmask_b32_e32 v16, v16, v17, vcc
	v_rsq_f32_e32 v16, v16
	s_nop 0
	v_mul_f32_e32 v17, 0x45800000, v16
	v_cndmask_b32_e32 v16, v16, v17, vcc
	v_fmamk_f32 v32, v32, 0x3c000000, v158
	v_cmp_gt_f32_e32 vcc, s82, v32
	v_mul_f32_e32 v33, 0x4b800000, v32
	s_nop 0
	v_cndmask_b32_e32 v32, v32, v33, vcc
	v_rsq_f32_e32 v32, v32
	s_nop 0
	v_mul_f32_e32 v33, 0x45800000, v32
	v_cndmask_b32_e32 v32, v32, v33, vcc
	v_fmamk_f32 v48, v48, 0x3c000000, v158
	v_cmp_gt_f32_e32 vcc, s82, v48
	v_mul_f32_e32 v49, 0x4b800000, v48
	s_nop 0
	v_cndmask_b32_e32 v48, v48, v49, vcc
	v_rsq_f32_e32 v48, v48
	s_nop 0
	v_mul_f32_e32 v49, 0x45800000, v48
	v_cndmask_b32_e32 v48, v48, v49, vcc
	v_fmamk_f32 v4, v4, 0x3c000000, v158
	v_cmp_gt_f32_e32 vcc, s82, v4
	v_mul_f32_e32 v5, 0x4b800000, v4
	s_nop 0
	v_cndmask_b32_e32 v4, v4, v5, vcc
	v_rsq_f32_e32 v4, v4
	s_nop 0
	v_mul_f32_e32 v5, 0x45800000, v4
	v_cndmask_b32_e32 v4, v4, v5, vcc
	v_fmamk_f32 v20, v20, 0x3c000000, v158
	v_cmp_gt_f32_e32 vcc, s82, v20
	v_mul_f32_e32 v21, 0x4b800000, v20
	s_nop 0
	v_cndmask_b32_e32 v20, v20, v21, vcc
	v_rsq_f32_e32 v20, v20
	s_nop 0
	v_mul_f32_e32 v21, 0x45800000, v20
	v_cndmask_b32_e32 v20, v20, v21, vcc
	v_fmamk_f32 v36, v36, 0x3c000000, v158
	v_cmp_gt_f32_e32 vcc, s82, v36
	v_mul_f32_e32 v37, 0x4b800000, v36
	s_nop 0
	v_cndmask_b32_e32 v36, v36, v37, vcc
	v_rsq_f32_e32 v36, v36
	s_nop 0
	v_mul_f32_e32 v37, 0x45800000, v36
	v_cndmask_b32_e32 v36, v36, v37, vcc
	v_fmamk_f32 v52, v52, 0x3c000000, v158
	v_cmp_gt_f32_e32 vcc, s82, v52
	v_mul_f32_e32 v53, 0x4b800000, v52
	s_nop 0
	v_cndmask_b32_e32 v52, v52, v53, vcc
	v_rsq_f32_e32 v52, v52
	s_nop 0
	v_mul_f32_e32 v53, 0x45800000, v52
	v_cndmask_b32_e32 v52, v52, v53, vcc
	v_fmamk_f32 v8, v8, 0x3c000000, v158
	v_cmp_gt_f32_e32 vcc, s82, v8
	v_mul_f32_e32 v9, 0x4b800000, v8
	s_nop 0
	v_cndmask_b32_e32 v8, v8, v9, vcc
	v_rsq_f32_e32 v8, v8
	s_nop 0
	v_mul_f32_e32 v9, 0x45800000, v8
	v_cndmask_b32_e32 v8, v8, v9, vcc
	v_fmamk_f32 v24, v24, 0x3c000000, v158
	v_cmp_gt_f32_e32 vcc, s82, v24
	v_mul_f32_e32 v25, 0x4b800000, v24
	s_nop 0
	v_cndmask_b32_e32 v24, v24, v25, vcc
	v_rsq_f32_e32 v24, v24
	s_nop 0
	v_mul_f32_e32 v25, 0x45800000, v24
	v_cndmask_b32_e32 v24, v24, v25, vcc
	v_fmamk_f32 v40, v40, 0x3c000000, v158
	v_cmp_gt_f32_e32 vcc, s82, v40
	v_mul_f32_e32 v41, 0x4b800000, v40
	s_nop 0
	v_cndmask_b32_e32 v40, v40, v41, vcc
	v_rsq_f32_e32 v40, v40
	s_nop 0
; __device__ __forceinline__ unsigned cvt_pk_bf16(float lo, float hi) { unsigned r; asm volatile("v_cvt_pk_bf16_f32 %0, %1, %2" : "=v"(r) : "v"(lo), "v"(hi)); return r; }
; __device__ __forceinline__ void phase_attn_diff(const Params& p, char* lds) {
;     ...
;                     const float rs = rsqrtf(ss * (1.0f / 128.0f) + EPS);
;                     bf16_t* Or = Ow + (size_t)((r & 3) + 8 * (r >> 2)) * 1024;
;                     Or[0] = (bf16_t)(cvt_pk_bf16(v0 * rs * gs[0], 0.f) & 0xffffu); Or[32] = (bf16_t)(cvt_pk_bf16(v1 * rs * gs[1], 0.f) & 0xffffu);
;                     Or[64] = (bf16_t)(cvt_pk_bf16(v2 * rs * gs[2], 0.f) & 0xffffu); Or[96] = (bf16_t)(cvt_pk_bf16(v3 * rs * gs[3], 0.f) & 0xffffu);
	v_mul_f32_e32 v41, 0x45800000, v40
	v_cndmask_b32_e32 v40, v40, v41, vcc
	v_fmamk_f32 v56, v56, 0x3c000000, v158
	v_cmp_gt_f32_e32 vcc, s82, v56
	v_mul_f32_e32 v57, 0x4b800000, v56
	s_nop 0
	v_cndmask_b32_e32 v56, v56, v57, vcc
	v_rsq_f32_e32 v56, v56
	s_nop 0
	v_mul_f32_e32 v57, 0x45800000, v56
	v_cndmask_b32_e32 v56, v56, v57, vcc
	v_fmamk_f32 v12, v12, 0x3c000000, v158
	v_cmp_gt_f32_e32 vcc, s82, v12
	v_mul_f32_e32 v13, 0x4b800000, v12
	s_nop 0
	v_cndmask_b32_e32 v12, v12, v13, vcc
	v_rsq_f32_e32 v12, v12
	s_nop 0
	v_mul_f32_e32 v13, 0x45800000, v12
	v_cndmask_b32_e32 v12, v12, v13, vcc
	v_add_co_u32_e32 v66, vcc, s83, v30
	s_nop 1
	v_addc_co_u32_e32 v67, vcc, 0, v31, vcc
	v_add_co_u32_e32 v70, vcc, s54, v30
	s_nop 1
	v_addc_co_u32_e32 v71, vcc, 0, v31, vcc
	v_add_co_u32_e32 v74, vcc, s59, v30
	s_nop 1
	v_addc_co_u32_e32 v75, vcc, 0, v31, vcc
	v_add_co_u32_e32 v2, vcc, s67, v30
	s_nop 1
	v_addc_co_u32_e32 v3, vcc, 0, v31, vcc
	v_add_co_u32_e32 v18, vcc, s55, v30
	s_nop 1
	v_addc_co_u32_e32 v19, vcc, 0, v31, vcc
	v_add_co_u32_e32 v34, vcc, s58, v30
	s_nop 1
	v_addc_co_u32_e32 v35, vcc, 0, v31, vcc
	v_add_co_u32_e32 v50, vcc, s2, v30
	s_nop 1
	v_addc_co_u32_e32 v51, vcc, 0, v31, vcc
	v_mul_f32_e32 v84, v84, v64
	v_mul_f32_e32 v85, v85, v64
	v_mul_f32_e32 v86, v86, v64
	v_mul_f32_e32 v87, v87, v64
	v_mul_f32_e32 v88, v88, v68
	v_mul_f32_e32 v89, v89, v68
	v_mul_f32_e32 v90, v90, v68
	v_mul_f32_e32 v91, v91, v68
	v_mul_f32_e32 v92, v92, v72
	v_mul_f32_e32 v93, v93, v72
	v_mul_f32_e32 v94, v94, v72
	v_mul_f32_e32 v95, v95, v72
	v_mul_f32_e32 v100, v100, v0
	v_mul_f32_e32 v101, v101, v0
	v_mul_f32_e32 v102, v102, v0
	v_mul_f32_e32 v103, v103, v0
	v_mul_f32_e32 v104, v104, v16
	v_mul_f32_e32 v105, v105, v16
	v_mul_f32_e32 v106, v106, v16
	v_mul_f32_e32 v107, v107, v16
	v_mul_f32_e32 v108, v108, v32
	v_mul_f32_e32 v109, v109, v32
	v_mul_f32_e32 v110, v110, v32
	v_mul_f32_e32 v111, v111, v32
	v_mul_f32_e32 v112, v112, v48
	v_mul_f32_e32 v113, v113, v48
	v_mul_f32_e32 v114, v114, v48
	v_mul_f32_e32 v115, v115, v48
	v_mul_f32_e32 v116, v116, v4
	v_mul_f32_e32 v117, v117, v4
	v_mul_f32_e32 v118, v118, v4
	v_mul_f32_e32 v119, v119, v4
	v_mul_f32_e32 v120, v120, v20
	v_mul_f32_e32 v121, v121, v20
	v_mul_f32_e32 v122, v122, v20
	v_mul_f32_e32 v123, v123, v20
	v_mul_f32_e32 v124, v124, v36
	v_mul_f32_e32 v125, v125, v36
	v_mul_f32_e32 v126, v126, v36
	v_mul_f32_e32 v127, v127, v36
	v_mul_f32_e32 v128, v128, v52
	v_mul_f32_e32 v129, v129, v52
	v_mul_f32_e32 v130, v130, v52
	v_mul_f32_e32 v131, v131, v52
	v_mul_f32_e32 v132, v132, v8
	v_mul_f32_e32 v133, v133, v8
	v_mul_f32_e32 v134, v134, v8
	v_mul_f32_e32 v135, v135, v8
	v_mul_f32_e32 v136, v136, v24
	v_mul_f32_e32 v137, v137, v24
	v_mul_f32_e32 v138, v138, v24
	v_mul_f32_e32 v139, v139, v24
	v_mul_f32_e32 v140, v140, v40
	v_mul_f32_e32 v141, v141, v40
	v_mul_f32_e32 v142, v142, v40
	v_mul_f32_e32 v143, v143, v40
	v_mul_f32_e32 v144, v144, v56
	v_mul_f32_e32 v145, v145, v56
	v_mul_f32_e32 v146, v146, v56
	v_mul_f32_e32 v147, v147, v56
	v_mul_f32_e32 v148, v148, v12
	v_mul_f32_e32 v149, v149, v12
	v_mul_f32_e32 v150, v150, v12
	v_mul_f32_e32 v151, v151, v12
	v_mul_f32_e32 v84, v172, v84
	v_mul_f32_e32 v85, v173, v85
	v_mul_f32_e32 v86, v174, v86
	v_mul_f32_e32 v87, v175, v87
	v_mul_f32_e32 v88, v172, v88
	v_mul_f32_e32 v89, v173, v89
	v_mul_f32_e32 v90, v174, v90
	v_mul_f32_e32 v91, v175, v91
	v_mul_f32_e32 v92, v172, v92
	v_mul_f32_e32 v93, v173, v93
	v_mul_f32_e32 v94, v174, v94
	v_mul_f32_e32 v95, v175, v95
	v_mul_f32_e32 v100, v172, v100
	v_mul_f32_e32 v101, v173, v101
	v_mul_f32_e32 v102, v174, v102
	v_mul_f32_e32 v103, v175, v103
	v_mul_f32_e32 v104, v172, v104
	v_mul_f32_e32 v105, v173, v105
	v_mul_f32_e32 v106, v174, v106
	v_mul_f32_e32 v107, v175, v107
	v_mul_f32_e32 v108, v172, v108
	v_mul_f32_e32 v109, v173, v109
	v_mul_f32_e32 v110, v174, v110
	v_mul_f32_e32 v111, v175, v111
	v_mul_f32_e32 v112, v172, v112
	v_mul_f32_e32 v113, v173, v113
	v_mul_f32_e32 v114, v174, v114
	v_mul_f32_e32 v115, v175, v115
	v_mul_f32_e32 v116, v172, v116
	v_mul_f32_e32 v117, v173, v117
	v_mul_f32_e32 v118, v174, v118
	v_mul_f32_e32 v119, v175, v119
	v_mul_f32_e32 v120, v172, v120
	v_mul_f32_e32 v121, v173, v121
	v_mul_f32_e32 v122, v174, v122
	v_mul_f32_e32 v123, v175, v123
	v_mul_f32_e32 v124, v172, v124
	v_mul_f32_e32 v125, v173, v125
	v_mul_f32_e32 v126, v174, v126
	v_mul_f32_e32 v127, v175, v127
	v_mul_f32_e32 v128, v172, v128
	v_mul_f32_e32 v129, v173, v129
	v_mul_f32_e32 v130, v174, v130
	v_mul_f32_e32 v131, v175, v131
	v_mul_f32_e32 v132, v172, v132
	v_mul_f32_e32 v133, v173, v133
	v_mul_f32_e32 v134, v174, v134
	v_mul_f32_e32 v135, v175, v135
	v_mul_f32_e32 v136, v172, v136
	v_mul_f32_e32 v137, v173, v137
	v_mul_f32_e32 v138, v174, v138
	v_mul_f32_e32 v139, v175, v139
	v_mul_f32_e32 v140, v172, v140
	v_mul_f32_e32 v141, v173, v141
	v_mul_f32_e32 v142, v174, v142
	v_mul_f32_e32 v143, v175, v143
	v_mul_f32_e32 v144, v172, v144
	v_mul_f32_e32 v145, v173, v145
	v_mul_f32_e32 v146, v174, v146
	v_mul_f32_e32 v147, v175, v147
	v_mul_f32_e32 v148, v172, v148
	v_mul_f32_e32 v149, v173, v149
	v_mul_f32_e32 v150, v174, v150
	v_mul_f32_e32 v151, v175, v151
	v_cvt_pk_bf16_f32 v84, v84, v97
	v_cvt_pk_bf16_f32 v85, v85, v97
	v_cvt_pk_bf16_f32 v86, v86, v97
	v_cvt_pk_bf16_f32 v87, v87, v97
	v_cvt_pk_bf16_f32 v88, v88, v97
	v_cvt_pk_bf16_f32 v89, v89, v97
	v_cvt_pk_bf16_f32 v90, v90, v97
; __device__ __forceinline__ unsigned cvt_pk_bf16(float lo, float hi) { unsigned r; asm volatile("v_cvt_pk_bf16_f32 %0, %1, %2" : "=v"(r) : "v"(lo), "v"(hi)); return r; }
; __device__ __forceinline__ void phase_attn_diff(const Params& p, char* lds) {
;     ...
;                     bf16_t* Or = Ow + (size_t)((r & 3) + 8 * (r >> 2)) * 1024;
;                     Or[0] = (bf16_t)(cvt_pk_bf16(v0 * rs * gs[0], 0.f) & 0xffffu); Or[32] = (bf16_t)(cvt_pk_bf16(v1 * rs * gs[1], 0.f) & 0xffffu);
;                     Or[64] = (bf16_t)(cvt_pk_bf16(v2 * rs * gs[2], 0.f) & 0xffffu); Or[96] = (bf16_t)(cvt_pk_bf16(v3 * rs * gs[3], 0.f) & 0xffffu);
;                 }
	v_cvt_pk_bf16_f32 v91, v91, v97
	v_cvt_pk_bf16_f32 v92, v92, v97
	v_cvt_pk_bf16_f32 v93, v93, v97
	v_cvt_pk_bf16_f32 v94, v94, v97
	v_cvt_pk_bf16_f32 v95, v95, v97
	v_cvt_pk_bf16_f32 v100, v100, v97
	v_cvt_pk_bf16_f32 v101, v101, v97
	v_cvt_pk_bf16_f32 v102, v102, v97
	v_cvt_pk_bf16_f32 v103, v103, v97
	v_cvt_pk_bf16_f32 v104, v104, v97
	v_cvt_pk_bf16_f32 v105, v105, v97
	v_cvt_pk_bf16_f32 v106, v106, v97
	v_cvt_pk_bf16_f32 v107, v107, v97
	v_cvt_pk_bf16_f32 v108, v108, v97
	v_cvt_pk_bf16_f32 v109, v109, v97
	v_cvt_pk_bf16_f32 v110, v110, v97
	v_cvt_pk_bf16_f32 v111, v111, v97
	v_cvt_pk_bf16_f32 v112, v112, v97
	v_cvt_pk_bf16_f32 v113, v113, v97
	v_cvt_pk_bf16_f32 v114, v114, v97
	v_cvt_pk_bf16_f32 v115, v115, v97
	v_cvt_pk_bf16_f32 v116, v116, v97
	v_cvt_pk_bf16_f32 v117, v117, v97
	v_cvt_pk_bf16_f32 v118, v118, v97
	v_cvt_pk_bf16_f32 v119, v119, v97
	v_cvt_pk_bf16_f32 v120, v120, v97
	v_cvt_pk_bf16_f32 v121, v121, v97
	v_cvt_pk_bf16_f32 v122, v122, v97
	v_cvt_pk_bf16_f32 v123, v123, v97
	v_cvt_pk_bf16_f32 v124, v124, v97
	v_cvt_pk_bf16_f32 v125, v125, v97
	v_cvt_pk_bf16_f32 v126, v126, v97
	v_cvt_pk_bf16_f32 v127, v127, v97
	v_cvt_pk_bf16_f32 v128, v128, v97
	v_cvt_pk_bf16_f32 v129, v129, v97
	v_cvt_pk_bf16_f32 v130, v130, v97
	v_cvt_pk_bf16_f32 v131, v131, v97
	v_cvt_pk_bf16_f32 v132, v132, v97
	v_cvt_pk_bf16_f32 v133, v133, v97
	v_cvt_pk_bf16_f32 v134, v134, v97
	v_cvt_pk_bf16_f32 v135, v135, v97
	v_cvt_pk_bf16_f32 v136, v136, v97
	v_cvt_pk_bf16_f32 v137, v137, v97
	v_cvt_pk_bf16_f32 v138, v138, v97
	v_cvt_pk_bf16_f32 v139, v139, v97
	v_cvt_pk_bf16_f32 v140, v140, v97
	v_cvt_pk_bf16_f32 v141, v141, v97
	v_cvt_pk_bf16_f32 v142, v142, v97
	v_cvt_pk_bf16_f32 v143, v143, v97
	v_cvt_pk_bf16_f32 v144, v144, v97
	v_cvt_pk_bf16_f32 v145, v145, v97
	v_cvt_pk_bf16_f32 v146, v146, v97
	v_cvt_pk_bf16_f32 v147, v147, v97
	v_cvt_pk_bf16_f32 v148, v148, v97
	v_cvt_pk_bf16_f32 v149, v149, v97
	v_cvt_pk_bf16_f32 v150, v150, v97
	v_cvt_pk_bf16_f32 v151, v151, v97
	global_store_short v[30:31], v84, off nt
	global_store_short v[30:31], v85, off offset:64 nt
	global_store_short v[30:31], v86, off offset:128 nt
	global_store_short v[30:31], v87, off offset:192 nt
	global_store_short v[30:31], v88, off offset:2048 nt
	global_store_short v[30:31], v89, off offset:2112 nt
	global_store_short v[30:31], v90, off offset:2176 nt
	global_store_short v[30:31], v91, off offset:2240 nt
	global_store_short v[66:67], v92, off nt
	global_store_short v[66:67], v93, off offset:64 nt
	global_store_short v[66:67], v94, off offset:128 nt
	global_store_short v[66:67], v95, off offset:192 nt
	global_store_short v[66:67], v100, off offset:2048 nt
	global_store_short v[66:67], v101, off offset:2112 nt
	global_store_short v[66:67], v102, off offset:2176 nt
	global_store_short v[66:67], v103, off offset:2240 nt
	global_store_short v[70:71], v104, off nt
	global_store_short v[70:71], v105, off offset:64 nt
	global_store_short v[70:71], v106, off offset:128 nt
	global_store_short v[70:71], v107, off offset:192 nt
	global_store_short v[70:71], v108, off offset:2048 nt
	global_store_short v[70:71], v109, off offset:2112 nt
	global_store_short v[70:71], v110, off offset:2176 nt
	global_store_short v[70:71], v111, off offset:2240 nt
	global_store_short v[74:75], v112, off nt
	global_store_short v[74:75], v113, off offset:64 nt
	global_store_short v[74:75], v114, off offset:128 nt
	global_store_short v[74:75], v115, off offset:192 nt
	global_store_short v[74:75], v116, off offset:2048 nt
	global_store_short v[74:75], v117, off offset:2112 nt
	global_store_short v[74:75], v118, off offset:2176 nt
	global_store_short v[74:75], v119, off offset:2240 nt
	global_store_short v[2:3], v120, off nt
	global_store_short v[2:3], v121, off offset:64 nt
	global_store_short v[2:3], v122, off offset:128 nt
	global_store_short v[2:3], v123, off offset:192 nt
	global_store_short v[2:3], v124, off offset:2048 nt
	global_store_short v[2:3], v125, off offset:2112 nt
	global_store_short v[2:3], v126, off offset:2176 nt
	global_store_short v[2:3], v127, off offset:2240 nt
	global_store_short v[18:19], v128, off nt
	global_store_short v[18:19], v129, off offset:64 nt
	global_store_short v[18:19], v130, off offset:128 nt
	global_store_short v[18:19], v131, off offset:192 nt
	global_store_short v[18:19], v132, off offset:2048 nt
	global_store_short v[18:19], v133, off offset:2112 nt
	global_store_short v[18:19], v134, off offset:2176 nt
	global_store_short v[18:19], v135, off offset:2240 nt
	global_store_short v[34:35], v136, off nt
	global_store_short v[34:35], v137, off offset:64 nt
	global_store_short v[34:35], v138, off offset:128 nt
	global_store_short v[34:35], v139, off offset:192 nt
	global_store_short v[34:35], v140, off offset:2048 nt
	global_store_short v[34:35], v141, off offset:2112 nt
	global_store_short v[34:35], v142, off offset:2176 nt
	global_store_short v[34:35], v143, off offset:2240 nt
	global_store_short v[50:51], v144, off nt
	global_store_short v[50:51], v145, off offset:64 nt
	global_store_short v[50:51], v146, off offset:128 nt
	global_store_short v[50:51], v147, off offset:192 nt
	global_store_short v[50:51], v148, off offset:2048 nt
	global_store_short v[50:51], v149, off offset:2112 nt
	global_store_short v[50:51], v150, off offset:2176 nt
	global_store_short v[50:51], v151, off offset:2240 nt
	s_cbranch_execnz .LBB0_169
	s_branch .LBB0_192

; __device__ __forceinline__ unsigned cvt_pk_bf16(float lo, float hi) { unsigned r; asm volatile("v_cvt_pk_bf16_f32 %0, %1, %2" : "=v"(r) : "v"(lo), "v"(hi)); return r; }
; __device__ __forceinline__ int crow(int r, int hi) { return (r & 3) + 8 * (r >> 2) + 4 * hi; }
; template <int DQK, int DK1, int LDQ, int LDK, int LDKR, int LDV, int NQL, int SDEPTH>
; __device__ __forceinline__ void attn_core(const AttnArgs& a, char* lds, f32x16 (&o)[4]) {
;     ...
;     if (hi == 0) li_l[r32] = l_reg; asm volatile("s_waitcnt lgkmcnt(0)" ::: "memory");
; #pragma unroll
;     for (int r = 0; r < 16; ++r) { const float rl = __builtin_amdgcn_rcpf(li_l[crow(r, hi)]);
; #pragma unroll
;         for (int d = 0; d < 4; ++d) o[d][r] *= rl; }
;     __syncthreads();
; __device__ __forceinline__ void phase_attn_mla(const Params& p, char* lds) {
;     ...
;         bf16_t* Ow = O + (size_t)(row0 + wid * 32 + 4 * hi) * 1024 + h * 128 + r32;
;         asm volatile("" : "+v"(Ow));
; #pragma unroll
;         for (int r = 0; r < 16; ++r) { bf16_t* Or = Ow + (size_t)((r & 3) + 8 * (r >> 2)) * 1024;
; #pragma unroll
;             for (int d0 = 0; d0 < 4; ++d0) Or[d0 * 32] = (bf16_t)(cvt_pk_bf16(o[d0][r], 0.f) & 0xffffu); }
.LBB0_200:
	s_or_b64 exec, exec, s[14:15]
	s_waitcnt lgkmcnt(0)
	v_add_u32_e32 v72, v161, v96
	ds_read_b128 v[64:67], v72
	ds_read_b128 v[68:71], v72 offset:32
	s_lshl_b32 s12, s24, 8
	s_mov_b32 s13, s36
	v_mov_b32_e32 v161, v97
	s_waitcnt lgkmcnt(1)
	v_rcp_f32_e32 v64, v64
	v_rcp_f32_e32 v65, v65
	s_movk_i32 s3, 0x4000
	s_mov_b32 s2, 0xc000
	v_mul_f32_e32 v48, v48, v64
	v_mul_f32_e32 v32, v32, v64
	v_mul_f32_e32 v73, v16, v64
	v_mul_f32_e32 v64, v0, v64
	v_mul_f32_e32 v49, v49, v65
	v_rcp_f32_e32 v0, v66
	v_mul_f32_e32 v33, v33, v65
	v_mul_f32_e32 v66, v17, v65
	v_mul_f32_e32 v65, v1, v65
	v_rcp_f32_e32 v1, v67
	v_mul_f32_e32 v50, v50, v0
	v_mul_f32_e32 v34, v34, v0
	v_mul_f32_e32 v67, v18, v0
	v_mul_f32_e32 v74, v2, v0
	v_mul_f32_e32 v51, v51, v1
	s_waitcnt lgkmcnt(0)
	v_rcp_f32_e32 v0, v68
	v_mul_f32_e32 v35, v35, v1
	v_mul_f32_e32 v68, v19, v1
	v_mul_f32_e32 v75, v3, v1
	v_rcp_f32_e32 v1, v69
	v_mul_f32_e32 v52, v52, v0
	v_mul_f32_e32 v36, v36, v0
	v_mul_f32_e32 v20, v20, v0
	v_mul_f32_e32 v4, v4, v0
	v_mul_f32_e32 v53, v53, v1
	v_mul_f32_e32 v37, v37, v1
	v_mul_f32_e32 v21, v21, v1
	v_mul_f32_e32 v5, v5, v1
	ds_read_b128 v[0:3], v72 offset:64
	v_rcp_f32_e32 v16, v70
	v_rcp_f32_e32 v69, v71
	v_mul_f32_e32 v54, v54, v16
	v_mul_f32_e32 v38, v38, v16
	v_mul_f32_e32 v22, v22, v16
	v_mul_f32_e32 v6, v6, v16
	ds_read_b128 v[16:19], v72 offset:96
	s_waitcnt lgkmcnt(1)
	v_rcp_f32_e32 v0, v0
	v_rcp_f32_e32 v1, v1
	s_waitcnt lgkmcnt(0)
	s_barrier
	v_mul_f32_e32 v56, v56, v0
	v_mul_f32_e32 v40, v40, v0
	v_mul_f32_e32 v24, v24, v0
	v_mul_f32_e32 v8, v8, v0
	v_rcp_f32_e32 v0, v2
	v_mul_f32_e32 v57, v57, v1
	v_mul_f32_e32 v41, v41, v1
	v_mul_f32_e32 v25, v25, v1
	v_mul_f32_e32 v9, v9, v1
	v_rcp_f32_e32 v1, v3
	v_mul_f32_e32 v58, v58, v0
	v_mul_f32_e32 v42, v42, v0
	v_mul_f32_e32 v26, v26, v0
	v_mul_f32_e32 v10, v10, v0
	v_rcp_f32_e32 v0, v16
	v_mul_f32_e32 v59, v59, v1
	v_mul_f32_e32 v16, v43, v1
	v_mul_f32_e32 v27, v27, v1
	v_mul_f32_e32 v11, v11, v1
	v_rcp_f32_e32 v1, v17
	v_mul_f32_e32 v43, v60, v0
	v_mul_f32_e32 v17, v44, v0
	v_mul_f32_e32 v28, v28, v0
	v_mul_f32_e32 v12, v12, v0
	v_rcp_f32_e32 v0, v18
	v_mul_f32_e32 v44, v61, v1
	v_mul_f32_e32 v18, v45, v1
	v_mul_f32_e32 v29, v29, v1
	v_mul_f32_e32 v13, v13, v1
	v_rcp_f32_e32 v1, v19
	v_mul_f32_e32 v45, v62, v0
	v_mul_f32_e32 v19, v46, v0
	v_mul_f32_e32 v30, v30, v0
	v_mul_f32_e32 v14, v14, v0
	v_add_u32_e32 v0, s23, v180
	v_mul_f32_e32 v46, v63, v1
	v_mul_f32_e32 v47, v47, v1
	v_mul_f32_e32 v31, v31, v1
	v_mul_f32_e32 v15, v15, v1
	v_ashrrev_i32_e32 v1, 31, v0
	v_lshlrev_b64 v[0:1], 11, v[0:1]
	v_lshl_add_u64 v[0:1], s[16:17], 0, v[0:1]
	v_lshl_add_u64 v[0:1], v[0:1], 0, s[12:13]
	v_lshl_add_u64 v[0:1], v[0:1], 0, v[160:161]
	v_cvt_pk_bf16_f32 v2, v48, v97
	global_store_short v[0:1], v2, off nt
	v_cvt_pk_bf16_f32 v2, v32, v97
	global_store_short v[0:1], v2, off offset:64 nt
	v_cvt_pk_bf16_f32 v2, v73, v97
	global_store_short v[0:1], v2, off offset:128 nt
	v_cvt_pk_bf16_f32 v2, v64, v97
	global_store_short v[0:1], v2, off offset:192 nt
	v_cvt_pk_bf16_f32 v2, v49, v97
	global_store_short v[0:1], v2, off offset:2048 nt
	v_cvt_pk_bf16_f32 v2, v33, v97
	global_store_short v[0:1], v2, off offset:2112 nt
	v_cvt_pk_bf16_f32 v2, v66, v97
	global_store_short v[0:1], v2, off offset:2176 nt
	v_cvt_pk_bf16_f32 v2, v65, v97
	global_store_short v[0:1], v2, off offset:2240 nt
	v_add_co_u32_e32 v2, vcc, s83, v0
	v_cvt_pk_bf16_f32 v32, v50, v97
	v_mul_f32_e32 v55, v55, v69
	s_nop 0
	v_addc_co_u32_e32 v3, vcc, 0, v1, vcc
	global_store_short v[2:3], v32, off nt
	v_cvt_pk_bf16_f32 v32, v34, v97
	global_store_short v[2:3], v32, off offset:64 nt
	v_cvt_pk_bf16_f32 v32, v67, v97
	global_store_short v[2:3], v32, off offset:128 nt
	v_cvt_pk_bf16_f32 v32, v74, v97
	global_store_short v[2:3], v32, off offset:192 nt
	v_cvt_pk_bf16_f32 v32, v51, v97
	global_store_short v[2:3], v32, off offset:2048 nt
	v_cvt_pk_bf16_f32 v32, v35, v97
	global_store_short v[2:3], v32, off offset:2112 nt
	v_cvt_pk_bf16_f32 v32, v68, v97
	global_store_short v[2:3], v32, off offset:2176 nt
	v_cvt_pk_bf16_f32 v32, v75, v97
	global_store_short v[2:3], v32, off offset:2240 nt
	v_add_co_u32_e32 v2, vcc, s3, v0
	v_cvt_pk_bf16_f32 v32, v52, v97
	v_mul_f32_e32 v39, v39, v69
	s_nop 0
	v_addc_co_u32_e32 v3, vcc, 0, v1, vcc
	global_store_short v[2:3], v32, off nt
	v_cvt_pk_bf16_f32 v32, v36, v97
	global_store_short v[2:3], v32, off offset:64 nt
	v_cvt_pk_bf16_f32 v20, v20, v97
; __device__ __forceinline__ unsigned cvt_pk_bf16(float lo, float hi) { unsigned r; asm volatile("v_cvt_pk_bf16_f32 %0, %1, %2" : "=v"(r) : "v"(lo), "v"(hi)); return r; }
; __device__ __forceinline__ void phase_attn_mla(const Params& p, char* lds) {
;     ...
;         bf16_t* Ow = O + (size_t)(row0 + wid * 32 + 4 * hi) * 1024 + h * 128 + r32;
;         asm volatile("" : "+v"(Ow));
; #pragma unroll
;         for (int r = 0; r < 16; ++r) { bf16_t* Or = Ow + (size_t)((r & 3) + 8 * (r >> 2)) * 1024;
; #pragma unroll
;             for (int d0 = 0; d0 < 4; ++d0) Or[d0 * 32] = (bf16_t)(cvt_pk_bf16(o[d0][r], 0.f) & 0xffffu); }
;     }
	global_store_short v[2:3], v20, off offset:128 nt
	v_cvt_pk_bf16_f32 v4, v4, v97
	global_store_short v[2:3], v4, off offset:192 nt
	v_cvt_pk_bf16_f32 v4, v53, v97
	global_store_short v[2:3], v4, off offset:2048 nt
	v_cvt_pk_bf16_f32 v4, v37, v97
	global_store_short v[2:3], v4, off offset:2112 nt
	v_cvt_pk_bf16_f32 v4, v21, v97
	global_store_short v[2:3], v4, off offset:2176 nt
	v_cvt_pk_bf16_f32 v4, v5, v97
	global_store_short v[2:3], v4, off offset:2240 nt
	v_add_co_u32_e32 v2, vcc, s59, v0
	v_cvt_pk_bf16_f32 v4, v54, v97
	v_mul_f32_e32 v23, v23, v69
	s_nop 0
	v_addc_co_u32_e32 v3, vcc, 0, v1, vcc
	global_store_short v[2:3], v4, off nt
	v_cvt_pk_bf16_f32 v4, v38, v97
	global_store_short v[2:3], v4, off offset:64 nt
	v_cvt_pk_bf16_f32 v4, v22, v97
	global_store_short v[2:3], v4, off offset:128 nt
	v_cvt_pk_bf16_f32 v4, v6, v97
	global_store_short v[2:3], v4, off offset:192 nt
	v_cvt_pk_bf16_f32 v4, v55, v97
	global_store_short v[2:3], v4, off offset:2048 nt
	v_cvt_pk_bf16_f32 v4, v39, v97
	global_store_short v[2:3], v4, off offset:2112 nt
	v_cvt_pk_bf16_f32 v4, v23, v97
	v_mul_f32_e32 v7, v7, v69
	global_store_short v[2:3], v4, off offset:2176 nt
	v_cvt_pk_bf16_f32 v4, v7, v97
	global_store_short v[2:3], v4, off offset:2240 nt
	v_add_co_u32_e32 v2, vcc, s67, v0
	v_cvt_pk_bf16_f32 v4, v56, v97
	s_mov_b32 s3, 0x9000
	s_nop 0
	v_addc_co_u32_e32 v3, vcc, 0, v1, vcc
	global_store_short v[2:3], v4, off nt
	v_cvt_pk_bf16_f32 v4, v40, v97
	global_store_short v[2:3], v4, off offset:64 nt
	v_cvt_pk_bf16_f32 v4, v24, v97
	global_store_short v[2:3], v4, off offset:128 nt
	v_cvt_pk_bf16_f32 v4, v8, v97
	global_store_short v[2:3], v4, off offset:192 nt
	v_cvt_pk_bf16_f32 v4, v57, v97
	global_store_short v[2:3], v4, off offset:2048 nt
	v_cvt_pk_bf16_f32 v4, v41, v97
	global_store_short v[2:3], v4, off offset:2112 nt
	v_cvt_pk_bf16_f32 v4, v25, v97
	global_store_short v[2:3], v4, off offset:2176 nt
	v_cvt_pk_bf16_f32 v4, v9, v97
	global_store_short v[2:3], v4, off offset:2240 nt
	v_add_co_u32_e32 v2, vcc, s3, v0
	v_cvt_pk_bf16_f32 v4, v58, v97
	s_mov_b32 s3, 0xd000
	s_nop 0
	v_addc_co_u32_e32 v3, vcc, 0, v1, vcc
	global_store_short v[2:3], v4, off nt
	v_cvt_pk_bf16_f32 v4, v42, v97
	global_store_short v[2:3], v4, off offset:64 nt
	v_cvt_pk_bf16_f32 v4, v26, v97
	global_store_short v[2:3], v4, off offset:128 nt
	v_cvt_pk_bf16_f32 v4, v10, v97
	global_store_short v[2:3], v4, off offset:192 nt
	v_cvt_pk_bf16_f32 v4, v59, v97
	global_store_short v[2:3], v4, off offset:2048 nt
	v_cvt_pk_bf16_f32 v4, v16, v97
	global_store_short v[2:3], v4, off offset:2112 nt
	v_cvt_pk_bf16_f32 v4, v27, v97
	global_store_short v[2:3], v4, off offset:2176 nt
	v_cvt_pk_bf16_f32 v4, v11, v97
	global_store_short v[2:3], v4, off offset:2240 nt
	v_add_co_u32_e32 v2, vcc, s2, v0
	v_cvt_pk_bf16_f32 v4, v43, v97
	s_nop 1
	v_addc_co_u32_e32 v3, vcc, 0, v1, vcc
	global_store_short v[2:3], v4, off nt
	v_cvt_pk_bf16_f32 v4, v17, v97
	global_store_short v[2:3], v4, off offset:64 nt
	v_cvt_pk_bf16_f32 v4, v28, v97
	global_store_short v[2:3], v4, off offset:128 nt
	v_cvt_pk_bf16_f32 v4, v12, v97
	global_store_short v[2:3], v4, off offset:192 nt
	v_cvt_pk_bf16_f32 v4, v44, v97
	global_store_short v[2:3], v4, off offset:2048 nt
	v_cvt_pk_bf16_f32 v4, v18, v97
	global_store_short v[2:3], v4, off offset:2112 nt
	v_cvt_pk_bf16_f32 v4, v29, v97
	v_add_co_u32_e32 v0, vcc, s3, v0
	global_store_short v[2:3], v4, off offset:2176 nt
	v_cvt_pk_bf16_f32 v4, v13, v97
	global_store_short v[2:3], v4, off offset:2240 nt
	v_cvt_pk_bf16_f32 v2, v45, v97
	v_addc_co_u32_e32 v1, vcc, 0, v1, vcc
	global_store_short v[0:1], v2, off nt
	v_cvt_pk_bf16_f32 v2, v19, v97
	global_store_short v[0:1], v2, off offset:64 nt
	v_cvt_pk_bf16_f32 v2, v30, v97
	global_store_short v[0:1], v2, off offset:128 nt
	v_cvt_pk_bf16_f32 v2, v14, v97
	global_store_short v[0:1], v2, off offset:192 nt
	v_cvt_pk_bf16_f32 v2, v46, v97
	global_store_short v[0:1], v2, off offset:2048 nt
	v_cvt_pk_bf16_f32 v2, v47, v97
	global_store_short v[0:1], v2, off offset:2112 nt
	v_cvt_pk_bf16_f32 v2, v31, v97
	global_store_short v[0:1], v2, off offset:2176 nt
	v_cvt_pk_bf16_f32 v2, v15, v97
	global_store_short v[0:1], v2, off offset:2240 nt
	s_load_dword s12, s[88:89], 0x10
	s_load_dword s14, s[88:89], 0x0
	s_waitcnt lgkmcnt(0)
	s_lshr_b32 s12, s12, 16
	s_cmp_lg_u32 s12, 0
	s_cselect_b64 s[12:13], -1, 0
	s_cmp_lg_u64 s[12:13], 0
	s_addc_u32 s22, s14, s22
	s_cmpk_gt_i32 s22, 0x47f
	s_cbranch_scc1 .LBB0_236

; __device__ __forceinline__ int v_st(int k, int c) { const int kk = (k & ~0xC) | ((k & 4) << 1) | ((k & 8) >> 1); return ((kk >> 3) * 4 + (c >> 5)) * 512 + ((kk & 7) * 32 + (c & 31)) * 2; }
; __device__ __forceinline__ int v_rd_base(int lane) { return ((lane & 3) << 3) | (((lane >> 2) & 3) << 6) | (((lane >> 4) & 1) << 5) | (((lane >> 5) & 1) << 8); }
; template <int DQK, int DK1, int LDQ, int LDK, int LDKR, int LDV, int NQL, int SDEPTH>
; __device__ __forceinline__ void attn_core(const AttnArgs& a, char* lds, f32x16 (&o)[4]) {
;     ...
;     char* QL = lds + 2 * SHM_V + 2 * SHM_K + 2048 + tid * 16;
;     { const bf16_t* Qw = a.Q + (long)(wid * 32 + r32) * LDQ + hi * 8;
; #pragma unroll
;       for (int d0 = 0; d0 < NQR; ++d0) qr[d0] = *(const bf16x8*)(Qw + d0 * 16);
; #pragma unroll
;       for (int d0 = NQR; d0 < ND0; ++d0) *(bf16x8*)(QL + (d0 - NQR) * 8192) = *(const bf16x8*)(Qw + d0 * 16); }
;     const int sr = tid >> 4, sc = (tid & 15) * 8, vst0 = v_st(sr, sc), vst1 = v_st(32 + sr, sc);
;     const int vb0 = (int)(uintptr_t)V_lds + v_rd_base(lane);
;     const bf16_t* kptr[KCH]; int kld[KCH], kwo[KCH];
; #pragma unroll
;     for (int c = 0; c < KCH; ++c) { const int idx = tid + c * 512, kr_ = idx / CPR, kc = (idx % CPR) * 8;
;         if (kc < DK1) { kptr[c] = a.Kn + (long)kr_ * LDK + kc; kld[c] = LDK; } else { kptr[c] = a.Kr + (long)kr_ * LDKR + (kc - DK1); kld[c] = LDKR; }
;         kwo[c] = kr_ * KP + ((kc * 2) ^ ((kr_ & 7) << 4)); }
;     struct { bf16x8 vs0, vs1, ks[KCH]; } sr_[SDEPTH];
;     int kb[4];
; #pragma unroll
;     for (int m = 0; m < 4; ++m) kb[m] = r32 * KP + ((m * 32 + hi * 16) ^ ((r32 & 7) << 4));
.LBB0_206:
	s_and_b32 s24, s14, 7
	s_mul_i32 s15, s23, 0xc00
	s_mul_hi_i32 s14, s23, 0xc00
	s_add_u32 s15, s4, s15
	s_addc_u32 s14, s5, s14
	s_mul_i32 s20, s24, 0x180
	s_add_u32 s20, s15, s20
	v_mov_b32_e32 v9, v159
	s_addc_u32 s21, s14, 0
	s_lshl_b32 s14, s24, 9
	v_ashrrev_i32_e32 v0, 1, v9
	v_bfe_u32 v2, v9, 5, 1
	v_bfi_b32 v3, s33, v0, v9
	v_mov_b64_e32 v[0:1], s[20:21]
	v_lshlrev_b32_e32 v8, 4, v9
	v_mad_i64_i32 v[0:1], s[20:21], v3, s77, v[0:1]
	v_lshlrev_b32_e32 v96, 4, v2
	v_lshl_add_u64 v[4:5], v[0:1], 0, v[96:97]
	v_add_u32_e32 v0, 0, v8
	global_load_dwordx4 v[126:129], v[4:5], off nt
	global_load_dwordx4 v[122:125], v[4:5], off offset:32 nt
	global_load_dwordx4 v[118:121], v[4:5], off offset:64 nt
	global_load_dwordx4 v[114:117], v[4:5], off offset:96 nt
	global_load_dwordx4 v[110:113], v[4:5], off offset:128 nt
	global_load_dwordx4 v[106:109], v[4:5], off offset:160 nt
	global_load_dwordx4 v[102:105], v[4:5], off offset:192 nt
	global_load_dwordx4 v[98:101], v[4:5], off offset:224 nt
	v_add_u32_e32 v181, 0x14800, v0
	global_load_dwordx4 v[64:67], v[4:5], off offset:256 nt
	global_load_dwordx4 v[68:71], v[4:5], off offset:288 nt
	global_load_dwordx4 v[72:75], v[4:5], off offset:320 nt
	global_load_dwordx4 v[76:79], v[4:5], off offset:352 nt
	s_add_u32 s14, s6, s14
	s_addc_u32 s15, s7, 0
	v_mul_hi_i32 v0, v9, s86
	v_lshrrev_b32_e32 v1, 31, v0
	v_ashrrev_i32_e32 v0, 2, v0
	v_add_u32_e32 v0, v0, v1
	v_mul_lo_u32 v1, v0, 24
	v_sub_u32_e32 v10, v9, v1
	v_lshlrev_b32_e32 v2, 3, v10
	v_cmp_lt_i32_e32 vcc, 15, v10
	v_ashrrev_i32_e32 v1, 31, v0
	s_and_saveexec_b64 s[20:21], vcc
	s_xor_b64 s[20:21], exec, s[20:21]
	v_lshlrev_b64 v[4:5], 7, v[0:1]
	v_lshl_add_u64 v[4:5], s[18:19], 0, v[4:5]
	v_mov_b32_e32 v3, v97
	s_movk_i32 s38, 0xff00
	v_lshl_add_u64 v[2:3], v[2:3], 1, v[4:5]
	s_mov_b32 s39, -1
	v_lshl_add_u64 v[162:163], v[2:3], 0, s[38:39]
	s_or_saveexec_b64 s[20:21], s[20:21]
	v_mov_b64_e32 v[164:165], 64
	s_xor_b64 exec, exec, s[20:21]
	v_lshlrev_b64 v[4:5], 12, v[0:1]
	v_lshl_add_u64 v[4:5], s[14:15], 0, v[4:5]
	v_ashrrev_i32_e32 v3, 31, v2
	v_lshl_add_u64 v[162:163], v[2:3], 1, v[4:5]
	v_mov_b64_e32 v[164:165], 0x800
	s_or_b64 exec, exec, s[20:21]
	v_add_u32_e32 v1, 0x200, v9
	v_mul_hi_i32 v2, v1, s86
	v_lshrrev_b32_e32 v3, 31, v2
	v_ashrrev_i32_e32 v2, 2, v2
	v_add_u32_e32 v4, v2, v3
	v_mul_lo_u32 v2, v4, 24
	v_sub_u32_e32 v11, v1, v2
	v_lshlrev_b32_e32 v2, 3, v11
	v_cmp_lt_i32_e32 vcc, 15, v11
	v_ashrrev_i32_e32 v5, 31, v4
	s_and_saveexec_b64 s[20:21], vcc
	s_xor_b64 s[20:21], exec, s[20:21]
	v_lshlrev_b64 v[6:7], 7, v[4:5]
	v_lshl_add_u64 v[6:7], s[18:19], 0, v[6:7]
	v_mov_b32_e32 v3, v97
	s_movk_i32 s38, 0xff00
	v_lshl_add_u64 v[2:3], v[2:3], 1, v[6:7]
	s_mov_b32 s39, -1
	v_lshl_add_u64 v[166:167], v[2:3], 0, s[38:39]
	s_or_saveexec_b64 s[20:21], s[20:21]
	v_mov_b64_e32 v[168:169], 64
	s_xor_b64 exec, exec, s[20:21]
	v_lshlrev_b64 v[6:7], 12, v[4:5]
	v_lshl_add_u64 v[6:7], s[14:15], 0, v[6:7]
	v_ashrrev_i32_e32 v3, 31, v2
	v_lshl_add_u64 v[166:167], v[2:3], 1, v[6:7]
	v_mov_b64_e32 v[168:169], 0x800
	s_or_b64 exec, exec, s[20:21]
	v_add_u32_e32 v1, 0x400, v9
	v_mul_hi_i32 v2, v1, s86
	v_lshrrev_b32_e32 v3, 31, v2
	v_ashrrev_i32_e32 v2, 2, v2
	v_add_u32_e32 v2, v2, v3
	v_mul_lo_u32 v3, v2, 24
	v_sub_u32_e32 v1, v1, v3
	v_lshlrev_b32_e32 v6, 3, v1
	v_cmp_lt_i32_e32 vcc, 15, v1
	v_ashrrev_i32_e32 v3, 31, v2
	s_and_saveexec_b64 s[20:21], vcc
	s_xor_b64 s[20:21], exec, s[20:21]
	v_lshlrev_b64 v[12:13], 7, v[2:3]
	v_lshl_add_u64 v[12:13], s[18:19], 0, v[12:13]
	v_mov_b32_e32 v7, v97
	s_movk_i32 s38, 0xff00
	v_lshl_add_u64 v[6:7], v[6:7], 1, v[12:13]
	s_mov_b32 s39, -1
	v_lshl_add_u64 v[170:171], v[6:7], 0, s[38:39]
	s_or_saveexec_b64 s[20:21], s[20:21]
	v_mov_b64_e32 v[172:173], 64
	s_xor_b64 exec, exec, s[20:21]
	v_lshlrev_b64 v[12:13], 12, v[2:3]
	v_lshl_add_u64 v[12:13], s[14:15], 0, v[12:13]
	v_ashrrev_i32_e32 v7, 31, v6
	v_lshl_add_u64 v[170:171], v[6:7], 1, v[12:13]
	v_mov_b64_e32 v[172:173], 0x800
	s_or_b64 exec, exec, s[20:21]
	v_mul_lo_u32 v3, v4, s84
	v_bitop3_b32 v4, v4, v11, 7 bitop3:0x6c
	v_ashrrev_i32_e32 v174, 4, v9
	v_lshl_add_u32 v20, v4, 4, v3
	v_and_b32_e32 v4, 0xfffff0, v174
	v_lshlrev_b32_e32 v5, 1, v174
	v_and_or_b32 v4, v5, 8, v4
	v_lshrrev_b32_e32 v5, 1, v174
	v_and_b32_e32 v6, 3, v174
	v_mul_lo_u32 v3, v0, s84
	v_bitop3_b32 v0, v0, v10, 7 bitop3:0x6c
	v_and_or_b32 v5, v5, 4, v6
	v_add_u32_e32 v6, 32, v174
	v_lshl_add_u32 v21, v0, 4, v3
	v_and_b32_e32 v0, 0x3fffffc0, v9
	s_add_i32 s20, 0, 0x14000
	v_and_b32_e32 v7, 0xfffff0, v6
	v_lshlrev_b32_e32 v6, 1, v6
	v_and_b32_e32 v52, 63, v9
	v_lshl_add_u32 v161, v0, 2, s20
	v_lshlrev_b32_e32 v0, 3, v9
	v_and_or_b32 v6, v6, 8, v7
	v_and_b32_e32 v3, 0x78, v0
	v_lshrrev_b32_e32 v4, 1, v4
	v_bfe_u32 v0, v0, 5, 2
	v_lshrrev_b32_e32 v6, 1, v6
	v_lshlrev_b32_e32 v7, 4, v52
	v_and_b32_e32 v51, 31, v9
	v_or_b32_e32 v4, v4, v0
	v_or_b32_e32 v0, v6, v0
	v_lshlrev_b32_e32 v6, 3, v52
	v_and_b32_e32 v7, 0xc0, v7
	v_lshlrev_b32_e32 v9, 1, v52
	v_and_or_b32 v7, v6, 24, v7
	v_and_b32_e32 v9, 32, v9
	v_and_b32_e32 v6, 0x100, v6
	v_or3_b32 v53, v7, v9, v6
	v_mul_lo_u32 v6, v2, s84
	v_bitop3_b32 v1, v2, v1, 7 bitop3:0x6c
	s_lshl_b32 s20, s68, 6
	v_lshlrev_b32_e32 v5, 6, v5
	v_lshlrev_b32_e32 v0, 9, v0
	v_lshl_add_u32 v22, v1, 4, v6
	v_and_b32_e32 v1, 48, v8
	s_sub_i32 s20, s28, s20
	v_or3_b32 v23, v0, v5, v1
	v_mul_u32_u24_e32 v0, 0x180, v51
	v_and_b32_e32 v2, 0x70, v8
	v_or_b32_e32 v6, 32, v96
	s_and_b64 s[12:13], s[12:13], exec
	v_bitop3_b32 v50, v6, v0, v2 bitop3:0xde
	v_or_b32_e32 v6, 64, v96
	s_cselect_b32 s12, s25, s20
	v_ashrrev_i32_e32 v175, 31, v174
	v_lshlrev_b32_e32 v4, 9, v4
	v_bitop3_b32 v62, v6, v0, v2 bitop3:0xde
	v_or_b32_e32 v6, 0x60, v96
	s_ashr_i32 s13, s12, 31
	v_lshl_add_u64 v[176:177], v[174:175], 0, 32
	v_bitop3_b32 v24, v96, v0, v2 bitop3:0xde
	v_bitop3_b32 v63, v6, v0, v2 bitop3:0xde
	v_or3_b32 v25, v4, v5, v1
	v_lshl_add_u64 v[0:1], v[174:175], 0, s[12:13]
	v_lshl_add_u64 v[4:5], v[176:177], 0, s[12:13]
	v_lshlrev_b64 v[0:1], 12, v[0:1]
	v_lshlrev_b64 v[4:5], 12, v[4:5]
	v_lshl_add_u64 v[0:1], s[14:15], 0, v[0:1]
	v_lshlrev_b32_e32 v48, 1, v3
	v_mov_b32_e32 v49, v97
	v_lshl_add_u64 v[4:5], s[14:15], 0, v[4:5]
	v_mad_i64_i32 v[8:9], s[20:21], v164, s12, 0
	v_mad_i64_i32 v[12:13], s[20:21], v168, s12, 0
	v_mad_i64_i32 v[16:17], s[20:21], v172, s12, 0
	v_lshl_add_u64 v[0:1], v[0:1], 0, v[48:49]
	v_lshl_add_u64 v[4:5], v[4:5], 0, v[48:49]
	v_lshl_add_u64 v[8:9], v[8:9], 1, v[162:163]
	v_lshl_add_u64 v[12:13], v[12:13], 1, v[166:167]
	v_lshl_add_u64 v[16:17], v[16:17], 1, v[170:171]
	global_load_dwordx4 v[0:3], v[0:1], off offset:256
	v_add_u32_e32 v186, 0, v25
	global_load_dwordx4 v[4:7], v[4:5], off offset:256
	v_add_u32_e32 v188, 0, v23
	global_load_dwordx4 v[8:11], v[8:9], off
	v_add_u32_e32 v194, 0, v21
	global_load_dwordx4 v[12:15], v[12:13], off
	v_add_u32_e32 v196, 0, v20
	global_load_dwordx4 v[16:19], v[16:17], off
	v_add_u32_e32 v198, 0, v22
	v_add_u32_e32 v184, 0, v24
	s_waitcnt vmcnt(0)
; #define SLOAD(i, j) do { const long rb_ = KROW(j); sr_[i].vs0 = *(const bf16x8*)(a.V + (rb_ + sr) * LDV + sc); sr_[i].vs1 = *(const bf16x8*)(a.V + (rb_ + 32 + sr) * LDV + sc); \
;     _Pragma("unroll") for (int c_ = 0; c_ < KCH; ++c_) sr_[i].ks[c_] = *(const bf16x8*)(kptr[c_] + rb_ * kld[c_]); } while (0)
; #define SWRITE(b, i) do { *(bf16x8*)(V_lds + (b) * SHM_V + vst0) = sr_[i].vs0; *(bf16x8*)(V_lds + (b) * SHM_V + vst1) = sr_[i].vs1; \
;     _Pragma("unroll") for (int c_ = 0; c_ < KCH; ++c_) *(bf16x8*)(K_lds + (b) * SHM_K + kwo[c_]) = sr_[i].ks[c_]; } while (0)
; template <int DQK, int DK1, int LDQ, int LDK, int LDKR, int LDV, int NQL, int SDEPTH>
; __device__ __forceinline__ void attn_core(const AttnArgs& a, char* lds, f32x16 (&o)[4]) {
;     ...
;     f32x16 pA0, pA1, pB0, pB1; float mnA, mnB, alA, alB; bf16x8 pa0, pa1, pa2, pa3; const int NT = a.NT;
;     constexpr int SE = 0, SO = SDEPTH - 1;
;     SLOAD(SE, 0); asm volatile("s_waitcnt vmcnt(0)" ::: "memory"); SWRITE(0, SE); __syncthreads();
;     QKT(pA0, pA1, K_lds); partialSM(pA0, pA1, m_reg, mnA, alA, a.C, a.thr);
	v_add_u32_e32 v192, 0, v50
	v_add_u32_e32 v190, 0, v62
	v_add_u32_e32 v173, 0, v63
	s_mov_b32 s37, s36
	s_mov_b32 s38, s36
	s_mov_b32 s39, s36
	s_mov_b32 s40, s36
	s_mov_b32 s41, s36
	s_mov_b32 s42, s36
	s_mov_b32 s43, s36
	s_mov_b32 s44, s36
	s_mov_b32 s45, s36
	s_mov_b32 s46, s36
	s_mov_b32 s47, s36
	s_mov_b32 s48, s36
	s_mov_b32 s49, s36
	s_mov_b32 s50, s36
	s_mov_b32 s51, s36
	v_lshl_add_u32 v165, v51, 2, v161
	v_lshl_add_u64 v[178:179], s[14:15], 0, v[48:49]
	s_mov_b32 s69, 2
	v_add_u32_e32 v216, 0xe000, v184
	v_add_u32_e32 v208, 0xe000, v192
	v_add_u32_e32 v206, 0xe000, v190
	v_add_u32_e32 v202, 0xe000, v173
	v_mov_b32_e32 v182, 0
	s_waitcnt vmcnt(0)
	ds_write_b128 v181, v[64:67]
	ds_write_b128 v181, v[68:71] offset:8192
	ds_write_b128 v181, v[72:75] offset:16384
	ds_write_b128 v181, v[76:79] offset:24576
	ds_write_b128 v186, v[0:3]
	ds_write_b128 v188, v[4:7]
	ds_write_b128 v194, v[8:11] offset:32768
	ds_write_b128 v196, v[12:15] offset:32768
	v_mov_b64_e32 v[0:1], s[36:37]
	ds_write_b128 v198, v[16:19] offset:32768
	s_waitcnt lgkmcnt(0)
	s_barrier
	ds_read_b128 v[16:19], v184 offset:32768
	ds_read_b128 v[20:23], v184 offset:45056
	s_waitcnt lgkmcnt(1)
	v_mfma_f32_32x32x16_bf16 v[32:47], v[16:19], v[126:129], 0
	ds_read_b128 v[54:57], v192 offset:32768
	ds_read_b128 v[58:61], v192 offset:45056
	v_mov_b64_e32 v[14:15], s[50:51]
	v_mov_b64_e32 v[2:3], s[38:39]
	v_mov_b64_e32 v[4:5], s[40:41]
	v_mov_b64_e32 v[6:7], s[42:43]
	v_mov_b64_e32 v[8:9], s[44:45]
	v_mov_b64_e32 v[10:11], s[46:47]
	s_waitcnt lgkmcnt(2)
	v_mfma_f32_32x32x16_bf16 v[16:31], v[20:23], v[126:129], 0
	v_mov_b64_e32 v[12:13], s[48:49]
	s_movk_i32 s37, 0x80
	s_waitcnt lgkmcnt(1)
	v_mfma_f32_32x32x16_bf16 v[32:47], v[54:57], v[122:125], v[32:47]
	s_waitcnt lgkmcnt(0)
	v_mfma_f32_32x32x16_bf16 v[16:31], v[58:61], v[122:125], v[16:31]
	ds_read_b128 v[54:57], v190 offset:32768
	ds_read_b128 v[58:61], v190 offset:45056
	s_waitcnt lgkmcnt(1)
	v_mfma_f32_32x32x16_bf16 v[32:47], v[54:57], v[118:121], v[32:47]
	s_waitcnt lgkmcnt(0)
	v_mfma_f32_32x32x16_bf16 v[16:31], v[58:61], v[118:121], v[16:31]
	ds_read_b128 v[54:57], v173 offset:32768
	ds_read_b128 v[58:61], v173 offset:45056
	s_waitcnt lgkmcnt(1)
	v_mfma_f32_32x32x16_bf16 v[32:47], v[54:57], v[114:117], v[32:47]
	s_waitcnt lgkmcnt(0)
	v_mfma_f32_32x32x16_bf16 v[16:31], v[58:61], v[114:117], v[16:31]
	ds_read_b128 v[54:57], v184 offset:32896
	ds_read_b128 v[58:61], v184 offset:45184
	s_waitcnt lgkmcnt(1)
	v_mfma_f32_32x32x16_bf16 v[32:47], v[54:57], v[110:113], v[32:47]
	s_waitcnt lgkmcnt(0)
	v_mfma_f32_32x32x16_bf16 v[16:31], v[58:61], v[110:113], v[16:31]
	ds_read_b128 v[54:57], v192 offset:32896
	ds_read_b128 v[58:61], v192 offset:45184
	s_waitcnt lgkmcnt(1)
	v_mfma_f32_32x32x16_bf16 v[32:47], v[54:57], v[106:109], v[32:47]
	s_waitcnt lgkmcnt(0)
	v_mfma_f32_32x32x16_bf16 v[16:31], v[58:61], v[106:109], v[16:31]
	ds_read_b128 v[54:57], v190 offset:32896
	ds_read_b128 v[58:61], v190 offset:45184
	s_waitcnt lgkmcnt(1)
	v_mfma_f32_32x32x16_bf16 v[32:47], v[54:57], v[102:105], v[32:47]
	s_waitcnt lgkmcnt(0)
	v_mfma_f32_32x32x16_bf16 v[16:31], v[58:61], v[102:105], v[16:31]
	ds_read_b128 v[54:57], v173 offset:32896
	ds_read_b128 v[58:61], v173 offset:45184
	s_waitcnt lgkmcnt(1)
	v_mfma_f32_32x32x16_bf16 v[32:47], v[54:57], v[98:101], v[32:47]
	s_waitcnt lgkmcnt(0)
	v_mfma_f32_32x32x16_bf16 v[16:31], v[58:61], v[98:101], v[16:31]
	ds_read_b128 v[54:57], v184 offset:33024
	ds_read_b128 v[58:61], v184 offset:45312
	ds_read_b128 v[62:65], v181
	s_waitcnt lgkmcnt(0)
	v_mfma_f32_32x32x16_bf16 v[32:47], v[54:57], v[62:65], v[32:47]
	v_mfma_f32_32x32x16_bf16 v[16:31], v[58:61], v[62:65], v[16:31]
	ds_read_b128 v[54:57], v192 offset:33024
	ds_read_b128 v[58:61], v192 offset:45312
	ds_read_b128 v[62:65], v181 offset:8192
	s_waitcnt lgkmcnt(0)
	v_mfma_f32_32x32x16_bf16 v[32:47], v[54:57], v[62:65], v[32:47]
	v_mfma_f32_32x32x16_bf16 v[16:31], v[58:61], v[62:65], v[16:31]
	ds_read_b128 v[54:57], v190 offset:33024
	ds_read_b128 v[58:61], v190 offset:45312
	ds_read_b128 v[62:65], v181 offset:16384
	s_waitcnt lgkmcnt(0)
	v_mfma_f32_32x32x16_bf16 v[32:47], v[54:57], v[62:65], v[32:47]
	v_mfma_f32_32x32x16_bf16 v[16:31], v[58:61], v[62:65], v[16:31]
	ds_read_b128 v[54:57], v173 offset:33024
	ds_read_b128 v[58:61], v173 offset:45312
	ds_read_b128 v[62:65], v181 offset:24576
	s_waitcnt lgkmcnt(0)
; #define SLOAD(i, j) do { const long rb_ = KROW(j); sr_[i].vs0 = *(const bf16x8*)(a.V + (rb_ + sr) * LDV + sc); sr_[i].vs1 = *(const bf16x8*)(a.V + (rb_ + 32 + sr) * LDV + sc); \
;     _Pragma("unroll") for (int c_ = 0; c_ < KCH; ++c_) sr_[i].ks[c_] = *(const bf16x8*)(kptr[c_] + rb_ * kld[c_]); } while (0)
; #define SWRITE(b, i) do { *(bf16x8*)(V_lds + (b) * SHM_V + vst0) = sr_[i].vs0; *(bf16x8*)(V_lds + (b) * SHM_V + vst1) = sr_[i].vs1; \
;     _Pragma("unroll") for (int c_ = 0; c_ < KCH; ++c_) *(bf16x8*)(K_lds + (b) * SHM_K + kwo[c_]) = sr_[i].ks[c_]; } while (0)
; __device__ __forceinline__ void partialSM(f32x16& p0, f32x16& p1, float& m_reg, float& mn, float& alpha, const float C, const float thr) {
;     float pmax = p0[0];
; #pragma unroll
;     for (int r = 1; r < 16; ++r) pmax = fmaxf(pmax, p0[r]);
; #pragma unroll
;     for (int r = 0; r < 16; ++r) pmax = fmaxf(pmax, p1[r]);
;     { auto rr = __builtin_amdgcn_permlane32_swap(__float_as_uint(pmax), __float_as_uint(pmax), false, false);
;       pmax = fmaxf(__uint_as_float(rr[0]), __uint_as_float(rr[1])); }
;     if (__builtin_expect(__all(pmax - m_reg <= thr), 1)) { mn = m_reg; alpha = 1.f; }
;     else { mn = fmaxf(m_reg, pmax); alpha = __builtin_amdgcn_exp2f((m_reg - mn) * C); m_reg = mn; }
;     const float mnC = -mn * C;
; #pragma unroll
;     for (int r = 0; r < 16; ++r) p0[r] = fmaf(p0[r], C, mnC);
; #pragma unroll
;     for (int r = 0; r < 16; ++r) p1[r] = fmaf(p1[r], C, mnC);
; #pragma unroll
;     for (int r = 0; r < 16; ++r) p0[r] = __builtin_amdgcn_exp2f(p0[r]);
; }
; template <int DQK, int DK1, int LDQ, int LDK, int LDKR, int LDV, int NQL, int SDEPTH>
; __device__ __forceinline__ void attn_core(const AttnArgs& a, char* lds, f32x16 (&o)[4]) {
;     ...
;     QKT(pA0, pA1, K_lds); partialSM(pA0, pA1, m_reg, mnA, alA, a.C, a.thr);
;     SLOAD(SO, 1); if (SDEPTH == 2 && 2 < NT) SLOAD(SE, 2);
;     SWRITE(1, SO); __syncthreads();
	v_mfma_f32_32x32x16_bf16 v[32:47], v[54:57], v[62:65], v[32:47]
	v_mfma_f32_32x32x16_bf16 v[16:31], v[58:61], v[62:65], v[16:31]
	s_nop 10
	v_max_f32_e32 v50, v33, v33
	v_max_f32_e32 v54, v32, v32
	v_max_f32_e32 v50, v54, v50
	v_max3_f32 v50, v50, v34, v35
	v_max3_f32 v50, v50, v36, v37
	v_max3_f32 v50, v50, v38, v39
	v_max3_f32 v50, v50, v40, v41
	v_max3_f32 v50, v50, v42, v43
	v_max3_f32 v50, v50, v44, v45
	v_max3_f32 v50, v50, v46, v47
	v_max3_f32 v50, v50, v16, v17
	v_max3_f32 v50, v50, v18, v19
	v_max3_f32 v50, v50, v20, v21
	v_max3_f32 v50, v50, v22, v23
	v_max3_f32 v50, v50, v24, v25
	v_max3_f32 v50, v50, v26, v27
	v_max3_f32 v50, v50, v28, v29
	v_max3_f32 v50, v50, v30, v31
	v_mov_b32_e32 v54, v50
	s_nop 1
	v_permlane32_swap_b32_e32 v50, v54
	v_max_f32_e32 v54, v54, v54
	v_max_f32_e32 v50, v50, v50
	v_max_f32_e32 v50, v50, v54
	v_add_f32_e32 v54, 0x7149f2ca, v50
	v_cmp_ge_f32_e32 vcc, s72, v54
	s_cmp_eq_u64 vcc, exec
	s_cselect_b64 vcc, -1, 0
	v_max_f32_e32 v50, 0xf149f2ca, v50
	v_cndmask_b32_e32 v204, v50, v193, vcc
	v_sub_f32_e32 v54, 0xf149f2ca, v50
	v_mul_f32_e32 v50, 0xbdd53b94, v204
	s_or_b32 s12, s12, 64
	v_fmamk_f32 v32, v32, 0x3dd53b94, v50
	v_fmamk_f32 v33, v33, 0x3dd53b94, v50
	s_ashr_i32 s13, s12, 31
	v_fmamk_f32 v36, v36, 0x3dd53b94, v50
	v_fmamk_f32 v37, v37, 0x3dd53b94, v50
	v_exp_f32_e32 v219, v32
	v_exp_f32_e32 v221, v33
	v_lshl_add_u64 v[32:33], v[174:175], 0, s[12:13]
	v_exp_f32_e32 v156, v36
	v_exp_f32_e32 v218, v37
	v_lshlrev_b64 v[32:33], 12, v[32:33]
	v_lshl_add_u64 v[36:37], v[176:177], 0, s[12:13]
	v_lshl_add_u64 v[32:33], s[14:15], 0, v[32:33]
	v_lshlrev_b64 v[36:37], 12, v[36:37]
	v_fmamk_f32 v34, v34, 0x3dd53b94, v50
	v_fmamk_f32 v35, v35, 0x3dd53b94, v50
	v_fmamk_f32 v40, v40, 0x3dd53b94, v50
	v_fmamk_f32 v41, v41, 0x3dd53b94, v50
	v_lshl_add_u64 v[32:33], v[32:33], 0, v[48:49]
	v_lshl_add_u64 v[36:37], s[14:15], 0, v[36:37]
	v_fmamk_f32 v38, v38, 0x3dd53b94, v50
	v_fmamk_f32 v39, v39, 0x3dd53b94, v50
	v_fmamk_f32 v44, v44, 0x3dd53b94, v50
	v_fmamk_f32 v45, v45, 0x3dd53b94, v50
	v_exp_f32_e32 v157, v34
	v_exp_f32_e32 v220, v35
	v_exp_f32_e32 v151, v40
	v_exp_f32_e32 v153, v41
	global_load_dwordx4 v[32:35], v[32:33], off offset:256
	v_lshl_add_u64 v[36:37], v[36:37], 0, v[48:49]
	v_mad_i64_i32 v[40:41], s[20:21], v164, s12, 0
	v_fmamk_f32 v42, v42, 0x3dd53b94, v50
	v_fmamk_f32 v43, v43, 0x3dd53b94, v50
	v_exp_f32_e32 v154, v38
	v_exp_f32_e32 v155, v39
	v_exp_f32_e32 v147, v44
	v_exp_f32_e32 v149, v45
	global_load_dwordx4 v[36:39], v[36:37], off offset:256
	v_lshl_add_u64 v[40:41], v[40:41], 1, v[162:163]
	v_mad_i64_i32 v[44:45], s[20:21], v168, s12, 0
	v_mul_f32_e32 v58, 0x3dd53b94, v54
	v_fmamk_f32 v46, v46, 0x3dd53b94, v50
	v_fmamk_f32 v47, v47, 0x3dd53b94, v50
	v_exp_f32_e32 v150, v42
	v_exp_f32_e32 v152, v43
	global_load_dwordx4 v[40:43], v[40:41], off
	v_lshl_add_u64 v[44:45], v[44:45], 1, v[166:167]
	v_mad_i64_i32 v[54:55], s[12:13], v172, s12, 0
	v_exp_f32_e32 v146, v46
	v_exp_f32_e32 v148, v47
	global_load_dwordx4 v[44:47], v[44:45], off
	v_lshl_add_u64 v[54:55], v[54:55], 1, v[170:171]
	global_load_dwordx4 v[54:57], v[54:55], off
	v_exp_f32_e32 v58, v58
	s_cmp_lg_u32 0, -1
	s_cselect_b32 s20, 0, 0
	v_add_u32_e32 v200, s20, v53
	s_addk_i32 s20, 0x4000
	s_waitcnt vmcnt(4)
	ds_write_b128 v186, v[32:35] offset:16384
	s_waitcnt vmcnt(3)
	ds_write_b128 v188, v[36:39] offset:16384
	s_waitcnt vmcnt(2)
	ds_write_b128 v194, v[40:43] offset:57344
	s_waitcnt vmcnt(1)
	ds_write_b128 v196, v[44:47] offset:57344
	s_waitcnt vmcnt(0)
	ds_write_b128 v198, v[54:57] offset:57344
	v_cndmask_b32_e64 v217, v58, 1.0, vcc
	v_pk_fma_f32 v[136:137], v[30:31], s[60:61], v[50:51] op_sel_hi:[1,0,0]
	v_pk_fma_f32 v[138:139], v[28:29], s[60:61], v[50:51] op_sel_hi:[1,0,0]
	v_pk_fma_f32 v[144:145], v[26:27], s[60:61], v[50:51] op_sel_hi:[1,0,0]
	v_pk_fma_f32 v[130:131], v[24:25], s[60:61], v[50:51] op_sel_hi:[1,0,0]
	v_pk_fma_f32 v[132:133], v[22:23], s[60:61], v[50:51] op_sel_hi:[1,0,0]
	v_pk_fma_f32 v[134:135], v[20:21], s[60:61], v[50:51] op_sel_hi:[1,0,0]
	v_pk_fma_f32 v[140:141], v[18:19], s[60:61], v[50:51] op_sel_hi:[1,0,0]
	v_pk_fma_f32 v[142:143], v[16:17], s[60:61], v[50:51] op_sel_hi:[1,0,0]
	v_cmp_gt_u32_e64 s[12:13], 32, v52
	v_add_u32_e32 v169, s20, v53
	v_mov_b64_e32 v[30:31], v[14:15]
	v_mov_b64_e32 v[46:47], v[14:15]
	v_mov_b64_e32 v[62:63], v[14:15]
	v_mov_b64_e32 v[28:29], v[12:13]
	v_mov_b64_e32 v[26:27], v[10:11]
	v_mov_b64_e32 v[24:25], v[8:9]
	v_mov_b64_e32 v[22:23], v[6:7]
	v_mov_b64_e32 v[20:21], v[4:5]
	v_mov_b64_e32 v[18:19], v[2:3]
	v_mov_b64_e32 v[16:17], v[0:1]
	v_mov_b64_e32 v[44:45], v[12:13]
	v_mov_b64_e32 v[42:43], v[10:11]
	v_mov_b64_e32 v[40:41], v[8:9]
	v_mov_b64_e32 v[38:39], v[6:7]
	v_mov_b64_e32 v[36:37], v[4:5]
	v_mov_b64_e32 v[34:35], v[2:3]
	v_mov_b64_e32 v[32:33], v[0:1]
	v_mov_b64_e32 v[60:61], v[12:13]
	v_mov_b64_e32 v[58:59], v[10:11]
	v_mov_b64_e32 v[56:57], v[8:9]
	v_mov_b64_e32 v[54:55], v[6:7]
	v_mov_b64_e32 v[52:53], v[4:5]
	v_mov_b64_e32 v[50:51], v[2:3]
	v_mov_b64_e32 v[48:49], v[0:1]
	s_waitcnt lgkmcnt(0)
	s_barrier
